# w_down residual epilogues (P9a prompt + P9b sample) restructured like w_o: software-pipelined x loads, permlane-coalesced loads/stores, AP block under the runtime flag
# baseline (speedup 1.0000x reference)
; DI u32x4 pack8(const float* v) { u32x4 w; w.x = pk2(v[0], v[1]); w.y = pk2(v[2], v[3]); w.z = pk2(v[4], v[5]); w.w = pk2(v[6], v[7]); return w; }
; #define xor16_32(s) xor16_32_l((s), fr + 16 * fq)
;     DI void operator()(AccRef acc, const Unit& u, int wr, int wc, int fr, int fq) const {
;     ...
;             for (int m = 0; m < 4; ++m) {
;                 const int row = rb + 16 * m;
;                 const float* xi = row < MP ? xin_p + (size_t)row * 1024 : xin_s + (size_t)(row - MP) * 1024;
;                 float s = 0.f;
; #pragma unroll
;                 for (int bj = 0; bj < 2; ++bj) {
;                     const int c = u.pn * 256 + bj * 128 + cl;
;                     float v[8];
; #pragma unroll
;                     for (int n = 0; n < 2; ++n) {
;                         const f32x4 x = *(const f32x4*)(xi + c + 4 * n);
;                         const f32x4 y = x + gt[bj][n] * acc[ai][bj][m][n];
;                         *(f32x4*)(xout + (size_t)row * 1024 + c + 4 * n) = y;
; #pragma unroll
;                         for (int j = 0; j < 4; ++j) { s += y[j] * y[j]; v[4 * n + j] = ap ? y[j] * gs[bj][n][j] : 0.f; }
;                     }
;                     if (ap) *(u32x4*)(ap + (size_t)row * 1024 + c) = pack8(v);
;                 }
;                 s = xor16_32(s);
;                 if (fq == 0) ssq[(size_t)row * 16 + u.pn * 4 + wc] = s;
.LBB0_1527:
	s_or_b64 exec, exec, s[4:5]
	s_sub_u32 s70, s18, 0x4000000
	s_subb_u32 s71, s19, 0
	s_cmp_ge_u32 s57, 64
	s_cselect_b32 s70, s70, s8
	s_cselect_b32 s71, s71, s9
	s_lshl_b32 s14, s56, 4
	s_add_u32 s72, s46, s14
	s_addc_u32 s73, s47, 0
	s_lshl_b32 s14, s41, 2
	s_add_u32 s72, s72, s14
	s_addc_u32 s73, s73, 0
	v_lshlrev_b32_e32 v213, 2, v172
	v_lshl_add_u32 v206, v176, 12, v213
	v_lshlrev_b32_e32 v213, 4, v194
	v_sub_u32_e32 v206, v206, v213
	v_mov_b32_e32 v207, v206
	v_lshlrev_b32_e32 v213, 11, v176
	v_lshl_add_u32 v208, v172, 1, v213
	v_lshlrev_b32_e32 v209, 6, v176
	v_lshlrev_b32_e32 v213, 2, v195
	v_lshl_add_u32 v213, v194, 6, v213
	v_xor_b32_e32 v214, 64, v213
	v_xor_b32_e32 v215, 0x80, v213
	global_load_dwordx4 v[232:235], v206, s[70:71] offset:64
	global_load_dwordx4 v[240:243], v206, s[70:71] offset:576
	global_load_dwordx4 v[228:231], v206, s[70:71]
	global_load_dwordx4 v[236:239], v206, s[70:71] offset:512
	v_add_u32_e32 v206, 0x10000, v206
	global_load_dwordx4 v[248:251], v206, s[70:71] offset:64
	global_load_dwordx4 v[220:223], v206, s[70:71] offset:576
	global_load_dwordx4 v[244:247], v206, s[70:71]
	global_load_dwordx4 v[216:219], v206, s[70:71] offset:512
	v_add_u32_e32 v206, 0x10000, v206
	s_waitcnt vmcnt(4)
	v_permlane32_swap_b32_e32 v228, v232
	v_permlane32_swap_b32_e32 v229, v233
	v_permlane32_swap_b32_e32 v230, v234
	v_permlane32_swap_b32_e32 v231, v235
	v_permlane32_swap_b32_e32 v236, v240
	v_permlane32_swap_b32_e32 v237, v241
	v_permlane32_swap_b32_e32 v238, v242
	v_permlane32_swap_b32_e32 v239, v243
	v_permlane16_swap_b32_e32 v228, v232
	v_permlane16_swap_b32_e32 v229, v233
	v_permlane16_swap_b32_e32 v230, v234
	v_permlane16_swap_b32_e32 v231, v235
	v_permlane16_swap_b32_e32 v236, v240
	v_permlane16_swap_b32_e32 v237, v241
	v_permlane16_swap_b32_e32 v238, v242
	v_permlane16_swap_b32_e32 v239, v243
	v_pk_fma_f32 v[140:141], v[140:141], v[144:145], v[228:229]
	v_pk_fma_f32 v[142:143], v[142:143], v[146:147], v[230:231]
	v_mul_f32_e32 v210, v141, v141
	v_fmac_f32_e32 v210, v140, v140
	v_fmac_f32_e32 v210, v142, v142
	v_fmac_f32_e32 v210, v143, v143
	v_pk_fma_f32 v[136:137], v[136:137], v[152:153], v[232:233]
	v_pk_fma_f32 v[138:139], v[138:139], v[154:155], v[234:235]
	v_fmac_f32_e32 v210, v136, v136
	v_fmac_f32_e32 v210, v137, v137
	v_fmac_f32_e32 v210, v138, v138
	v_fmac_f32_e32 v210, v139, v139
	v_pk_fma_f32 v[132:133], v[132:133], v[148:149], v[236:237]
	v_pk_fma_f32 v[134:135], v[134:135], v[150:151], v[238:239]
	v_fmac_f32_e32 v210, v132, v132
	v_fmac_f32_e32 v210, v133, v133
	v_fmac_f32_e32 v210, v134, v134
	v_fmac_f32_e32 v210, v135, v135
	v_pk_fma_f32 v[128:129], v[128:129], v[156:157], v[240:241]
	v_pk_fma_f32 v[130:131], v[130:131], v[158:159], v[242:243]
	v_fmac_f32_e32 v210, v128, v128
	v_fmac_f32_e32 v210, v129, v129
	v_fmac_f32_e32 v210, v130, v130
	v_fmac_f32_e32 v210, v131, v131
	s_cmp_lg_u64 s[2:3], 0
	s_cbranch_scc1 .Lnoap_C_1
	v_pk_mul_f32 v[228:229], v[64:65], v[140:141]
	v_pk_mul_f32 v[230:231], v[66:67], v[142:143]
	v_pk_mul_f32 v[232:233], v[72:73], v[136:137]
	v_pk_mul_f32 v[234:235], v[74:75], v[138:139]
	v_pk_mul_f32 v[236:237], v[68:69], v[132:133]
	v_pk_mul_f32 v[238:239], v[70:71], v[134:135]
	v_pk_mul_f32 v[240:241], v[76:77], v[128:129]
	v_pk_mul_f32 v[242:243], v[78:79], v[130:131]
	v_cvt_pk_bf16_f32 v228, v228, v229
	v_cvt_pk_bf16_f32 v229, v230, v231
	v_cvt_pk_bf16_f32 v230, v232, v233
	v_cvt_pk_bf16_f32 v231, v234, v235
	global_store_dwordx4 v208, v[228:231], s[42:43]
	v_cvt_pk_bf16_f32 v236, v236, v237
	v_cvt_pk_bf16_f32 v237, v238, v239
	v_cvt_pk_bf16_f32 v238, v240, v241
	v_cvt_pk_bf16_f32 v239, v242, v243
	global_store_dwordx4 v208, v[236:239], s[42:43] offset:256
.Lnoap_C_1:
	ds_bpermute_b32 v211, v214, v210
	v_permlane16_swap_b32_e32 v140, v136
	v_permlane16_swap_b32_e32 v141, v137
	v_permlane16_swap_b32_e32 v142, v138
	v_permlane16_swap_b32_e32 v143, v139
	v_permlane16_swap_b32_e32 v132, v128
	v_permlane16_swap_b32_e32 v133, v129
	v_permlane16_swap_b32_e32 v134, v130
	v_permlane16_swap_b32_e32 v135, v131
	v_permlane32_swap_b32_e32 v140, v136
	v_permlane32_swap_b32_e32 v141, v137
	v_permlane32_swap_b32_e32 v142, v138
	v_permlane32_swap_b32_e32 v143, v139
	v_permlane32_swap_b32_e32 v132, v128
	v_permlane32_swap_b32_e32 v133, v129
	v_permlane32_swap_b32_e32 v134, v130
	v_permlane32_swap_b32_e32 v135, v131
	global_store_dwordx4 v207, v[140:143], s[8:9]
	global_store_dwordx4 v207, v[136:139], s[8:9] offset:64
	global_store_dwordx4 v207, v[132:135], s[8:9] offset:512
	global_store_dwordx4 v207, v[128:131], s[8:9] offset:576
	v_add_u32_e32 v207, 0x10000, v207
	global_load_dwordx4 v[232:235], v206, s[70:71] offset:64
	global_load_dwordx4 v[240:243], v206, s[70:71] offset:576
	global_load_dwordx4 v[228:231], v206, s[70:71]
	global_load_dwordx4 v[236:239], v206, s[70:71] offset:512
	s_waitcnt lgkmcnt(0)
	v_add_f32_e32 v211, v210, v211
	ds_bpermute_b32 v212, v215, v211
	v_add_u32_e32 v208, 0x8000, v208
	s_waitcnt lgkmcnt(0)
	v_add_f32_e32 v211, v211, v212
	s_mov_b64 exec, 0xffff
	global_store_dword v209, v211, s[72:73]
	s_mov_b64 exec, -1
	v_add_u32_e32 v209, 0x400, v209
	s_waitcnt vmcnt(9)
	v_permlane32_swap_b32_e32 v244, v248
	v_permlane32_swap_b32_e32 v245, v249
	v_permlane32_swap_b32_e32 v246, v250
	v_permlane32_swap_b32_e32 v247, v251
	v_permlane32_swap_b32_e32 v216, v220
	v_permlane32_swap_b32_e32 v217, v221
	v_permlane32_swap_b32_e32 v218, v222
	v_permlane32_swap_b32_e32 v219, v223
	v_permlane16_swap_b32_e32 v244, v248
	v_permlane16_swap_b32_e32 v245, v249
	v_permlane16_swap_b32_e32 v246, v250
	v_permlane16_swap_b32_e32 v247, v251
	v_permlane16_swap_b32_e32 v216, v220
	v_permlane16_swap_b32_e32 v217, v221
	v_permlane16_swap_b32_e32 v218, v222
	v_permlane16_swap_b32_e32 v219, v223
	v_pk_fma_f32 v[124:125], v[124:125], v[144:145], v[244:245]
	v_pk_fma_f32 v[126:127], v[126:127], v[146:147], v[246:247]
	v_mul_f32_e32 v210, v125, v125
	v_fmac_f32_e32 v210, v124, v124
	v_fmac_f32_e32 v210, v126, v126
	v_fmac_f32_e32 v210, v127, v127
	v_pk_fma_f32 v[120:121], v[120:121], v[152:153], v[248:249]
	v_pk_fma_f32 v[122:123], v[122:123], v[154:155], v[250:251]
	v_fmac_f32_e32 v210, v120, v120
	v_fmac_f32_e32 v210, v121, v121
	v_fmac_f32_e32 v210, v122, v122
	v_fmac_f32_e32 v210, v123, v123
	v_pk_fma_f32 v[116:117], v[116:117], v[148:149], v[216:217]
	v_pk_fma_f32 v[118:119], v[118:119], v[150:151], v[218:219]
	v_fmac_f32_e32 v210, v116, v116
	v_fmac_f32_e32 v210, v117, v117
	v_fmac_f32_e32 v210, v118, v118
	v_fmac_f32_e32 v210, v119, v119
	v_pk_fma_f32 v[112:113], v[112:113], v[156:157], v[220:221]
	v_pk_fma_f32 v[114:115], v[114:115], v[158:159], v[222:223]
	v_fmac_f32_e32 v210, v112, v112
	v_fmac_f32_e32 v210, v113, v113
	v_fmac_f32_e32 v210, v114, v114
	v_fmac_f32_e32 v210, v115, v115
	s_cmp_lg_u64 s[2:3], 0
	s_cbranch_scc1 .Lnoap_C_2
; DI u32x4 pack8(const float* v) { u32x4 w; w.x = pk2(v[0], v[1]); w.y = pk2(v[2], v[3]); w.z = pk2(v[4], v[5]); w.w = pk2(v[6], v[7]); return w; }
; #define xor16_32(s) xor16_32_l((s), fr + 16 * fq)
;     DI void operator()(AccRef acc, const Unit& u, int wr, int wc, int fr, int fq) const {
;     ...
;             for (int m = 0; m < 4; ++m) {
;                 const int row = rb + 16 * m;
;                 const float* xi = row < MP ? xin_p + (size_t)row * 1024 : xin_s + (size_t)(row - MP) * 1024;
;                 float s = 0.f;
; #pragma unroll
;                 for (int bj = 0; bj < 2; ++bj) {
;                     const int c = u.pn * 256 + bj * 128 + cl;
;                     float v[8];
; #pragma unroll
;                     for (int n = 0; n < 2; ++n) {
;                         const f32x4 x = *(const f32x4*)(xi + c + 4 * n);
;                         const f32x4 y = x + gt[bj][n] * acc[ai][bj][m][n];
;                         *(f32x4*)(xout + (size_t)row * 1024 + c + 4 * n) = y;
; #pragma unroll
;                         for (int j = 0; j < 4; ++j) { s += y[j] * y[j]; v[4 * n + j] = ap ? y[j] * gs[bj][n][j] : 0.f; }
;                     }
;                     if (ap) *(u32x4*)(ap + (size_t)row * 1024 + c) = pack8(v);
;                 }
;                 s = xor16_32(s);
;                 if (fq == 0) ssq[(size_t)row * 16 + u.pn * 4 + wc] = s;
	v_pk_mul_f32 v[244:245], v[64:65], v[124:125]
	v_pk_mul_f32 v[246:247], v[66:67], v[126:127]
	v_pk_mul_f32 v[248:249], v[72:73], v[120:121]
	v_pk_mul_f32 v[250:251], v[74:75], v[122:123]
	v_pk_mul_f32 v[216:217], v[68:69], v[116:117]
	v_pk_mul_f32 v[218:219], v[70:71], v[118:119]
	v_pk_mul_f32 v[220:221], v[76:77], v[112:113]
	v_pk_mul_f32 v[222:223], v[78:79], v[114:115]
	v_cvt_pk_bf16_f32 v244, v244, v245
	v_cvt_pk_bf16_f32 v245, v246, v247
	v_cvt_pk_bf16_f32 v246, v248, v249
	v_cvt_pk_bf16_f32 v247, v250, v251
	global_store_dwordx4 v208, v[244:247], s[42:43]
	v_cvt_pk_bf16_f32 v216, v216, v217
	v_cvt_pk_bf16_f32 v217, v218, v219
	v_cvt_pk_bf16_f32 v218, v220, v221
	v_cvt_pk_bf16_f32 v219, v222, v223
	global_store_dwordx4 v208, v[216:219], s[42:43] offset:256
.Lnoap_C_2:
	ds_bpermute_b32 v211, v214, v210
	v_permlane16_swap_b32_e32 v124, v120
	v_permlane16_swap_b32_e32 v125, v121
	v_permlane16_swap_b32_e32 v126, v122
	v_permlane16_swap_b32_e32 v127, v123
	v_permlane16_swap_b32_e32 v116, v112
	v_permlane16_swap_b32_e32 v117, v113
	v_permlane16_swap_b32_e32 v118, v114
	v_permlane16_swap_b32_e32 v119, v115
	v_permlane32_swap_b32_e32 v124, v120
	v_permlane32_swap_b32_e32 v125, v121
	v_permlane32_swap_b32_e32 v126, v122
	v_permlane32_swap_b32_e32 v127, v123
	v_permlane32_swap_b32_e32 v116, v112
	v_permlane32_swap_b32_e32 v117, v113
	v_permlane32_swap_b32_e32 v118, v114
	v_permlane32_swap_b32_e32 v119, v115
	global_store_dwordx4 v207, v[124:127], s[8:9]
	global_store_dwordx4 v207, v[120:123], s[8:9] offset:64
	global_store_dwordx4 v207, v[116:119], s[8:9] offset:512
	global_store_dwordx4 v207, v[112:115], s[8:9] offset:576
	v_add_u32_e32 v207, 0x10000, v207
	v_add_u32_e32 v206, 0x10000, v206
	global_load_dwordx4 v[248:251], v206, s[70:71] offset:64
	global_load_dwordx4 v[220:223], v206, s[70:71] offset:576
	global_load_dwordx4 v[244:247], v206, s[70:71]
	global_load_dwordx4 v[216:219], v206, s[70:71] offset:512
	s_waitcnt lgkmcnt(0)
	v_add_f32_e32 v211, v210, v211
	ds_bpermute_b32 v212, v215, v211
	v_add_u32_e32 v208, 0x8000, v208
	s_waitcnt lgkmcnt(0)
	v_add_f32_e32 v211, v211, v212
	s_mov_b64 exec, 0xffff
	global_store_dword v209, v211, s[72:73]
	s_mov_b64 exec, -1
	v_add_u32_e32 v209, 0x400, v209
	s_waitcnt vmcnt(10)
	v_permlane32_swap_b32_e32 v228, v232
	v_permlane32_swap_b32_e32 v229, v233
	v_permlane32_swap_b32_e32 v230, v234
	v_permlane32_swap_b32_e32 v231, v235
	v_permlane32_swap_b32_e32 v236, v240
	v_permlane32_swap_b32_e32 v237, v241
	v_permlane32_swap_b32_e32 v238, v242
	v_permlane32_swap_b32_e32 v239, v243
	v_permlane16_swap_b32_e32 v228, v232
	v_permlane16_swap_b32_e32 v229, v233
	v_permlane16_swap_b32_e32 v230, v234
	v_permlane16_swap_b32_e32 v231, v235
	v_permlane16_swap_b32_e32 v236, v240
	v_permlane16_swap_b32_e32 v237, v241
	v_permlane16_swap_b32_e32 v238, v242
	v_permlane16_swap_b32_e32 v239, v243
	v_pk_fma_f32 v[108:109], v[108:109], v[144:145], v[228:229]
	v_pk_fma_f32 v[110:111], v[110:111], v[146:147], v[230:231]
	v_mul_f32_e32 v210, v109, v109
	v_fmac_f32_e32 v210, v108, v108
	v_fmac_f32_e32 v210, v110, v110
	v_fmac_f32_e32 v210, v111, v111
	v_pk_fma_f32 v[104:105], v[104:105], v[152:153], v[232:233]
	v_pk_fma_f32 v[106:107], v[106:107], v[154:155], v[234:235]
	v_fmac_f32_e32 v210, v104, v104
	v_fmac_f32_e32 v210, v105, v105
	v_fmac_f32_e32 v210, v106, v106
	v_fmac_f32_e32 v210, v107, v107
	v_pk_fma_f32 v[100:101], v[100:101], v[148:149], v[236:237]
	v_pk_fma_f32 v[102:103], v[102:103], v[150:151], v[238:239]
	v_fmac_f32_e32 v210, v100, v100
	v_fmac_f32_e32 v210, v101, v101
	v_fmac_f32_e32 v210, v102, v102
	v_fmac_f32_e32 v210, v103, v103
	v_pk_fma_f32 v[96:97], v[96:97], v[156:157], v[240:241]
	v_pk_fma_f32 v[98:99], v[98:99], v[158:159], v[242:243]
	v_fmac_f32_e32 v210, v96, v96
	v_fmac_f32_e32 v210, v97, v97
	v_fmac_f32_e32 v210, v98, v98
	v_fmac_f32_e32 v210, v99, v99
	s_cmp_lg_u64 s[2:3], 0
	s_cbranch_scc1 .Lnoap_C_3
	v_pk_mul_f32 v[228:229], v[64:65], v[108:109]
	v_pk_mul_f32 v[230:231], v[66:67], v[110:111]
	v_pk_mul_f32 v[232:233], v[72:73], v[104:105]
	v_pk_mul_f32 v[234:235], v[74:75], v[106:107]
	v_pk_mul_f32 v[236:237], v[68:69], v[100:101]
	v_pk_mul_f32 v[238:239], v[70:71], v[102:103]
	v_pk_mul_f32 v[240:241], v[76:77], v[96:97]
	v_pk_mul_f32 v[242:243], v[78:79], v[98:99]
	v_cvt_pk_bf16_f32 v228, v228, v229
	v_cvt_pk_bf16_f32 v229, v230, v231
	v_cvt_pk_bf16_f32 v230, v232, v233
	v_cvt_pk_bf16_f32 v231, v234, v235
	global_store_dwordx4 v208, v[228:231], s[42:43]
	v_cvt_pk_bf16_f32 v236, v236, v237
	v_cvt_pk_bf16_f32 v237, v238, v239
	v_cvt_pk_bf16_f32 v238, v240, v241
	v_cvt_pk_bf16_f32 v239, v242, v243
	global_store_dwordx4 v208, v[236:239], s[42:43] offset:256
; DI u32x4 pack8(const float* v) { u32x4 w; w.x = pk2(v[0], v[1]); w.y = pk2(v[2], v[3]); w.z = pk2(v[4], v[5]); w.w = pk2(v[6], v[7]); return w; }
; #define xor16_32(s) xor16_32_l((s), fr + 16 * fq)
;     DI void operator()(AccRef acc, const Unit& u, int wr, int wc, int fr, int fq) const {
;     ...
;         for (int ai = 0; ai < 2; ++ai) {
;             const int rb = u.pm * 256 + ai * 128 + wr * 64 + fr;
;             int mb, pos0, kv0; row_info(rb, mb, pos0, kv0);
;             f32x4 gt[2][2], gs[2][2];
; #pragma unroll
;             for (int bj = 0; bj < 2; ++bj)
; #pragma unroll
;                 for (int n = 0; n < 2; ++n) {
;                     const int c = u.pn * 256 + bj * 128 + cl + 4 * n;
;                     gt[bj][n] = *(const f32x4*)(gate + (size_t)mb * 6144 + c);
;                     if (ap) { const f32x4 g = *(const f32x4*)(gn + c), s = *(const f32x4*)(scn + (size_t)mb * 6144 + c); gs[bj][n] = g * (s + 1.f); }
;     ...
;             for (int m = 0; m < 4; ++m) {
;                 const int row = rb + 16 * m;
;                 const float* xi = row < MP ? xin_p + (size_t)row * 1024 : xin_s + (size_t)(row - MP) * 1024;
;                 float s = 0.f;
; #pragma unroll
;                 for (int bj = 0; bj < 2; ++bj) {
;                     const int c = u.pn * 256 + bj * 128 + cl;
;                     float v[8];
; #pragma unroll
;                     for (int n = 0; n < 2; ++n) {
;                         const f32x4 x = *(const f32x4*)(xi + c + 4 * n);
;                         const f32x4 y = x + gt[bj][n] * acc[ai][bj][m][n];
;                         *(f32x4*)(xout + (size_t)row * 1024 + c + 4 * n) = y;
; #pragma unroll
;                         for (int j = 0; j < 4; ++j) { s += y[j] * y[j]; v[4 * n + j] = ap ? y[j] * gs[bj][n][j] : 0.f; }
;                     }
;                     if (ap) *(u32x4*)(ap + (size_t)row * 1024 + c) = pack8(v);
;                 }
;                 s = xor16_32(s);
;                 if (fq == 0) ssq[(size_t)row * 16 + u.pn * 4 + wc] = s;
.Lnoap_C_3:
	ds_bpermute_b32 v211, v214, v210
	v_permlane16_swap_b32_e32 v108, v104
	v_permlane16_swap_b32_e32 v109, v105
	v_permlane16_swap_b32_e32 v110, v106
	v_permlane16_swap_b32_e32 v111, v107
	v_permlane16_swap_b32_e32 v100, v96
	v_permlane16_swap_b32_e32 v101, v97
	v_permlane16_swap_b32_e32 v102, v98
	v_permlane16_swap_b32_e32 v103, v99
	v_permlane32_swap_b32_e32 v108, v104
	v_permlane32_swap_b32_e32 v109, v105
	v_permlane32_swap_b32_e32 v110, v106
	v_permlane32_swap_b32_e32 v111, v107
	v_permlane32_swap_b32_e32 v100, v96
	v_permlane32_swap_b32_e32 v101, v97
	v_permlane32_swap_b32_e32 v102, v98
	v_permlane32_swap_b32_e32 v103, v99
	global_store_dwordx4 v207, v[108:111], s[8:9]
	global_store_dwordx4 v207, v[104:107], s[8:9] offset:64
	global_store_dwordx4 v207, v[100:103], s[8:9] offset:512
	global_store_dwordx4 v207, v[96:99], s[8:9] offset:576
	v_add_u32_e32 v207, 0x10000, v207
	v_add_u32_e32 v206, 0x50000, v206
	global_load_dwordx4 v[232:235], v206, s[70:71] offset:64
	global_load_dwordx4 v[240:243], v206, s[70:71] offset:576
	global_load_dwordx4 v[228:231], v206, s[70:71]
	global_load_dwordx4 v[236:239], v206, s[70:71] offset:512
	s_waitcnt lgkmcnt(0)
	v_add_f32_e32 v211, v210, v211
	ds_bpermute_b32 v212, v215, v211
	v_add_u32_e32 v208, 0x8000, v208
	s_waitcnt lgkmcnt(0)
	v_add_f32_e32 v211, v211, v212
	s_mov_b64 exec, 0xffff
	global_store_dword v209, v211, s[72:73]
	s_mov_b64 exec, -1
	v_add_u32_e32 v209, 0x400, v209
	s_waitcnt vmcnt(10)
	v_permlane32_swap_b32_e32 v244, v248
	v_permlane32_swap_b32_e32 v245, v249
	v_permlane32_swap_b32_e32 v246, v250
	v_permlane32_swap_b32_e32 v247, v251
	v_permlane32_swap_b32_e32 v216, v220
	v_permlane32_swap_b32_e32 v217, v221
	v_permlane32_swap_b32_e32 v218, v222
	v_permlane32_swap_b32_e32 v219, v223
	v_permlane16_swap_b32_e32 v244, v248
	v_permlane16_swap_b32_e32 v245, v249
	v_permlane16_swap_b32_e32 v246, v250
	v_permlane16_swap_b32_e32 v247, v251
	v_permlane16_swap_b32_e32 v216, v220
	v_permlane16_swap_b32_e32 v217, v221
	v_permlane16_swap_b32_e32 v218, v222
	v_permlane16_swap_b32_e32 v219, v223
	v_pk_fma_f32 v[92:93], v[92:93], v[144:145], v[244:245]
	v_pk_fma_f32 v[94:95], v[94:95], v[146:147], v[246:247]
	v_mul_f32_e32 v210, v93, v93
	v_fmac_f32_e32 v210, v92, v92
	v_fmac_f32_e32 v210, v94, v94
	v_fmac_f32_e32 v210, v95, v95
	v_pk_fma_f32 v[88:89], v[88:89], v[152:153], v[248:249]
	v_pk_fma_f32 v[90:91], v[90:91], v[154:155], v[250:251]
	v_fmac_f32_e32 v210, v88, v88
	v_fmac_f32_e32 v210, v89, v89
	v_fmac_f32_e32 v210, v90, v90
	v_fmac_f32_e32 v210, v91, v91
	v_pk_fma_f32 v[84:85], v[84:85], v[148:149], v[216:217]
	v_pk_fma_f32 v[86:87], v[86:87], v[150:151], v[218:219]
	v_fmac_f32_e32 v210, v84, v84
	v_fmac_f32_e32 v210, v85, v85
	v_fmac_f32_e32 v210, v86, v86
	v_fmac_f32_e32 v210, v87, v87
	v_pk_fma_f32 v[80:81], v[80:81], v[156:157], v[220:221]
	v_pk_fma_f32 v[82:83], v[82:83], v[158:159], v[222:223]
	v_fmac_f32_e32 v210, v80, v80
	v_fmac_f32_e32 v210, v81, v81
	v_fmac_f32_e32 v210, v82, v82
	v_fmac_f32_e32 v210, v83, v83
	s_cmp_lg_u64 s[2:3], 0
	s_cbranch_scc1 .Lnoap_C_4
	v_pk_mul_f32 v[244:245], v[64:65], v[92:93]
	v_pk_mul_f32 v[246:247], v[66:67], v[94:95]
	v_pk_mul_f32 v[248:249], v[72:73], v[88:89]
	v_pk_mul_f32 v[250:251], v[74:75], v[90:91]
	v_pk_mul_f32 v[216:217], v[68:69], v[84:85]
	v_pk_mul_f32 v[218:219], v[70:71], v[86:87]
	v_pk_mul_f32 v[220:221], v[76:77], v[80:81]
	v_pk_mul_f32 v[222:223], v[78:79], v[82:83]
	v_cvt_pk_bf16_f32 v244, v244, v245
	v_cvt_pk_bf16_f32 v245, v246, v247
	v_cvt_pk_bf16_f32 v246, v248, v249
	v_cvt_pk_bf16_f32 v247, v250, v251
	global_store_dwordx4 v208, v[244:247], s[42:43]
	v_cvt_pk_bf16_f32 v216, v216, v217
	v_cvt_pk_bf16_f32 v217, v218, v219
	v_cvt_pk_bf16_f32 v218, v220, v221
	v_cvt_pk_bf16_f32 v219, v222, v223
	global_store_dwordx4 v208, v[216:219], s[42:43] offset:256
.Lnoap_C_4:
	ds_bpermute_b32 v211, v214, v210
	v_permlane16_swap_b32_e32 v92, v88
	v_permlane16_swap_b32_e32 v93, v89
	v_permlane16_swap_b32_e32 v94, v90
	v_permlane16_swap_b32_e32 v95, v91
	v_permlane16_swap_b32_e32 v84, v80
	v_permlane16_swap_b32_e32 v85, v81
	v_permlane16_swap_b32_e32 v86, v82
	v_permlane16_swap_b32_e32 v87, v83
	v_permlane32_swap_b32_e32 v92, v88
	v_permlane32_swap_b32_e32 v93, v89
	v_permlane32_swap_b32_e32 v94, v90
	v_permlane32_swap_b32_e32 v95, v91
	v_permlane32_swap_b32_e32 v84, v80
	v_permlane32_swap_b32_e32 v85, v81
	v_permlane32_swap_b32_e32 v86, v82
	v_permlane32_swap_b32_e32 v87, v83
	global_store_dwordx4 v207, v[92:95], s[8:9]
	global_store_dwordx4 v207, v[88:91], s[8:9] offset:64
	global_store_dwordx4 v207, v[84:87], s[8:9] offset:512
	global_store_dwordx4 v207, v[80:83], s[8:9] offset:576
	v_add_u32_e32 v207, 0x50000, v207
	v_add_u32_e32 v206, 0x10000, v206
	global_load_dwordx4 v[248:251], v206, s[70:71] offset:64
	global_load_dwordx4 v[220:223], v206, s[70:71] offset:576
	global_load_dwordx4 v[244:247], v206, s[70:71]
	global_load_dwordx4 v[216:219], v206, s[70:71] offset:512
	s_waitcnt lgkmcnt(0)
	v_add_f32_e32 v211, v210, v211
	ds_bpermute_b32 v212, v215, v211
	v_add_u32_e32 v208, 0x28000, v208
	s_waitcnt lgkmcnt(0)
	v_add_f32_e32 v211, v211, v212
	s_mov_b64 exec, 0xffff
	global_store_dword v209, v211, s[72:73]
	s_mov_b64 exec, -1
	v_add_u32_e32 v209, 0x1400, v209
	v_add_u32_e32 v224, 0xffffc080, v176
	v_add_u32_e32 v96, 0x80, v176
	s_waitcnt lgkmcnt(0)
	v_lshrrev_b32_e32 v81, 6, v224
	v_cmp_gt_i32_e32 vcc, s94, v96
	v_ashrrev_i32_e32 v80, 11, v96
	v_add_u32_e32 v81, 8, v81
	v_cndmask_b32_e32 v84, v81, v80, vcc
	v_mov_b64_e32 v[80:81], s[28:29]
	v_mad_i64_i32 v[80:81], s[12:13], v84, s75, v[80:81]
	v_mov_b64_e32 v[82:83], s[30:31]
	v_lshl_add_u64 v[92:93], v[172:173], 2, v[80:81]
	v_mad_i64_i32 v[84:85], s[12:13], v84, s75, v[82:83]
	global_load_dwordx4 v[80:83], v[92:93], off
	s_movk_i32 s6, 0x3fff
	v_cmp_lt_i32_e64 s[6:7], s6, v96
	s_and_b64 vcc, exec, s[2:3]
	s_cbranch_vccnz .LBB0_1567
	v_lshl_add_u64 v[64:65], v[84:85], 0, v[174:175]
	global_load_dwordx4 v[64:67], v[64:65], off
	s_nop 0
	global_load_dwordx4 v[86:89], v[178:179], off
	s_waitcnt vmcnt(1)
	v_pk_add_f32 v[66:67], v[66:67], 1.0 op_sel_hi:[1,0]
	v_pk_add_f32 v[64:65], v[64:65], 1.0 op_sel_hi:[1,0]
	s_waitcnt vmcnt(0)
	v_pk_mul_f32 v[66:67], v[88:89], v[66:67]
	v_pk_mul_f32 v[64:65], v[86:87], v[64:65]
	global_load_dwordx4 v[88:91], v[92:93], off offset:16
	s_and_b64 vcc, exec, s[2:3]
	v_lshl_add_u64 v[98:99], v[172:173], 2, v[84:85]
	s_cbranch_vccz .LBB0_1568

; DI u32x4 pack8(const float* v) { u32x4 w; w.x = pk2(v[0], v[1]); w.y = pk2(v[2], v[3]); w.z = pk2(v[4], v[5]); w.w = pk2(v[6], v[7]); return w; }
; #define xor16_32(s) xor16_32_l((s), fr + 16 * fq)
;     DI void operator()(AccRef acc, const Unit& u, int wr, int wc, int fr, int fq) const {
;     ...
;             for (int m = 0; m < 4; ++m) {
;                 const int row = rb + 16 * m;
;                 const float* xi = row < MP ? xin_p + (size_t)row * 1024 : xin_s + (size_t)(row - MP) * 1024;
;                 float s = 0.f;
; #pragma unroll
;                 for (int bj = 0; bj < 2; ++bj) {
;                     const int c = u.pn * 256 + bj * 128 + cl;
;                     float v[8];
; #pragma unroll
;                     for (int n = 0; n < 2; ++n) {
;                         const f32x4 x = *(const f32x4*)(xi + c + 4 * n);
;                         const f32x4 y = x + gt[bj][n] * acc[ai][bj][m][n];
;                         *(f32x4*)(xout + (size_t)row * 1024 + c + 4 * n) = y;
; #pragma unroll
;                         for (int j = 0; j < 4; ++j) { s += y[j] * y[j]; v[4 * n + j] = ap ? y[j] * gs[bj][n][j] : 0.f; }
;                     }
;                     if (ap) *(u32x4*)(ap + (size_t)row * 1024 + c) = pack8(v);
;                 }
;                 s = xor16_32(s);
;                 if (fq == 0) ssq[(size_t)row * 16 + u.pn * 4 + wc] = s;
;             }
.LBB0_1575:
	s_or_b64 exec, exec, s[6:7]
	s_waitcnt vmcnt(0)
	v_permlane32_swap_b32_e32 v228, v232
	v_permlane32_swap_b32_e32 v229, v233
	v_permlane32_swap_b32_e32 v230, v234
	v_permlane32_swap_b32_e32 v231, v235
	v_permlane32_swap_b32_e32 v236, v240
	v_permlane32_swap_b32_e32 v237, v241
	v_permlane32_swap_b32_e32 v238, v242
	v_permlane32_swap_b32_e32 v239, v243
	v_permlane16_swap_b32_e32 v228, v232
	v_permlane16_swap_b32_e32 v229, v233
	v_permlane16_swap_b32_e32 v230, v234
	v_permlane16_swap_b32_e32 v231, v235
	v_permlane16_swap_b32_e32 v236, v240
	v_permlane16_swap_b32_e32 v237, v241
	v_permlane16_swap_b32_e32 v238, v242
	v_permlane16_swap_b32_e32 v239, v243
	v_pk_fma_f32 v[60:61], v[60:61], v[80:81], v[228:229]
	v_pk_fma_f32 v[62:63], v[62:63], v[82:83], v[230:231]
	v_mul_f32_e32 v210, v61, v61
	v_fmac_f32_e32 v210, v60, v60
	v_fmac_f32_e32 v210, v62, v62
	v_fmac_f32_e32 v210, v63, v63
	v_pk_fma_f32 v[56:57], v[56:57], v[88:89], v[232:233]
	v_pk_fma_f32 v[58:59], v[58:59], v[90:91], v[234:235]
	v_fmac_f32_e32 v210, v56, v56
	v_fmac_f32_e32 v210, v57, v57
	v_fmac_f32_e32 v210, v58, v58
	v_fmac_f32_e32 v210, v59, v59
	v_pk_fma_f32 v[52:53], v[52:53], v[84:85], v[236:237]
	v_pk_fma_f32 v[54:55], v[54:55], v[86:87], v[238:239]
	v_fmac_f32_e32 v210, v52, v52
	v_fmac_f32_e32 v210, v53, v53
	v_fmac_f32_e32 v210, v54, v54
	v_fmac_f32_e32 v210, v55, v55
	v_pk_fma_f32 v[48:49], v[48:49], v[92:93], v[240:241]
	v_pk_fma_f32 v[50:51], v[50:51], v[94:95], v[242:243]
	v_fmac_f32_e32 v210, v48, v48
	v_fmac_f32_e32 v210, v49, v49
	v_fmac_f32_e32 v210, v50, v50
	v_fmac_f32_e32 v210, v51, v51
	s_cmp_lg_u64 s[2:3], 0
	s_cbranch_scc1 .Lnoap_C_5
	v_pk_mul_f32 v[228:229], v[64:65], v[60:61]
	v_pk_mul_f32 v[230:231], v[66:67], v[62:63]
	v_pk_mul_f32 v[232:233], v[72:73], v[56:57]
	v_pk_mul_f32 v[234:235], v[74:75], v[58:59]
	v_pk_mul_f32 v[236:237], v[68:69], v[52:53]
	v_pk_mul_f32 v[238:239], v[70:71], v[54:55]
	v_pk_mul_f32 v[240:241], v[76:77], v[48:49]
	v_pk_mul_f32 v[242:243], v[78:79], v[50:51]
	v_cvt_pk_bf16_f32 v228, v228, v229
	v_cvt_pk_bf16_f32 v229, v230, v231
	v_cvt_pk_bf16_f32 v230, v232, v233
	v_cvt_pk_bf16_f32 v231, v234, v235
	global_store_dwordx4 v208, v[228:231], s[42:43]
	v_cvt_pk_bf16_f32 v236, v236, v237
	v_cvt_pk_bf16_f32 v237, v238, v239
	v_cvt_pk_bf16_f32 v238, v240, v241
	v_cvt_pk_bf16_f32 v239, v242, v243
	global_store_dwordx4 v208, v[236:239], s[42:43] offset:256
.Lnoap_C_5:
	ds_bpermute_b32 v211, v214, v210
	v_permlane16_swap_b32_e32 v60, v56
	v_permlane16_swap_b32_e32 v61, v57
	v_permlane16_swap_b32_e32 v62, v58
	v_permlane16_swap_b32_e32 v63, v59
	v_permlane16_swap_b32_e32 v52, v48
	v_permlane16_swap_b32_e32 v53, v49
	v_permlane16_swap_b32_e32 v54, v50
	v_permlane16_swap_b32_e32 v55, v51
	v_permlane32_swap_b32_e32 v60, v56
	v_permlane32_swap_b32_e32 v61, v57
	v_permlane32_swap_b32_e32 v62, v58
	v_permlane32_swap_b32_e32 v63, v59
	v_permlane32_swap_b32_e32 v52, v48
	v_permlane32_swap_b32_e32 v53, v49
	v_permlane32_swap_b32_e32 v54, v50
	v_permlane32_swap_b32_e32 v55, v51
	global_store_dwordx4 v207, v[60:63], s[8:9]
	global_store_dwordx4 v207, v[56:59], s[8:9] offset:64
	global_store_dwordx4 v207, v[52:55], s[8:9] offset:512
	global_store_dwordx4 v207, v[48:51], s[8:9] offset:576
	v_add_u32_e32 v207, 0x10000, v207
	v_add_u32_e32 v206, 0x10000, v206
	global_load_dwordx4 v[232:235], v206, s[70:71] offset:64
	global_load_dwordx4 v[240:243], v206, s[70:71] offset:576
	global_load_dwordx4 v[228:231], v206, s[70:71]
	global_load_dwordx4 v[236:239], v206, s[70:71] offset:512
	s_waitcnt lgkmcnt(0)
	v_add_f32_e32 v211, v210, v211
	ds_bpermute_b32 v212, v215, v211
	v_add_u32_e32 v208, 0x8000, v208
	s_waitcnt lgkmcnt(0)
	v_add_f32_e32 v211, v211, v212
	s_mov_b64 exec, 0xffff
	global_store_dword v209, v211, s[72:73]
	s_mov_b64 exec, -1
	v_add_u32_e32 v209, 0x400, v209
	v_permlane32_swap_b32_e32 v244, v248
	v_permlane32_swap_b32_e32 v245, v249
	v_permlane32_swap_b32_e32 v246, v250
	v_permlane32_swap_b32_e32 v247, v251
	v_permlane32_swap_b32_e32 v216, v220
	v_permlane32_swap_b32_e32 v217, v221
	v_permlane32_swap_b32_e32 v218, v222
	v_permlane32_swap_b32_e32 v219, v223
	v_permlane16_swap_b32_e32 v244, v248
	v_permlane16_swap_b32_e32 v245, v249
	v_permlane16_swap_b32_e32 v246, v250
	v_permlane16_swap_b32_e32 v247, v251
	v_permlane16_swap_b32_e32 v216, v220
	v_permlane16_swap_b32_e32 v217, v221
	v_permlane16_swap_b32_e32 v218, v222
	v_permlane16_swap_b32_e32 v219, v223
	v_pk_fma_f32 v[44:45], v[44:45], v[80:81], v[244:245]
	v_pk_fma_f32 v[46:47], v[46:47], v[82:83], v[246:247]
	v_mul_f32_e32 v210, v45, v45
	v_fmac_f32_e32 v210, v44, v44
	v_fmac_f32_e32 v210, v46, v46
	v_fmac_f32_e32 v210, v47, v47
	v_pk_fma_f32 v[40:41], v[40:41], v[88:89], v[248:249]
	v_pk_fma_f32 v[42:43], v[42:43], v[90:91], v[250:251]
	v_fmac_f32_e32 v210, v40, v40
	v_fmac_f32_e32 v210, v41, v41
	v_fmac_f32_e32 v210, v42, v42
	v_fmac_f32_e32 v210, v43, v43
	v_pk_fma_f32 v[36:37], v[36:37], v[84:85], v[216:217]
	v_pk_fma_f32 v[38:39], v[38:39], v[86:87], v[218:219]
	v_fmac_f32_e32 v210, v36, v36
	v_fmac_f32_e32 v210, v37, v37
	v_fmac_f32_e32 v210, v38, v38
	v_fmac_f32_e32 v210, v39, v39
	v_pk_fma_f32 v[32:33], v[32:33], v[92:93], v[220:221]
	v_pk_fma_f32 v[34:35], v[34:35], v[94:95], v[222:223]
	v_fmac_f32_e32 v210, v32, v32
	v_fmac_f32_e32 v210, v33, v33
	v_fmac_f32_e32 v210, v34, v34
	v_fmac_f32_e32 v210, v35, v35
	s_cmp_lg_u64 s[2:3], 0
	s_cbranch_scc1 .Lnoap_C_6
	v_pk_mul_f32 v[244:245], v[64:65], v[44:45]
	v_pk_mul_f32 v[246:247], v[66:67], v[46:47]
	v_pk_mul_f32 v[248:249], v[72:73], v[40:41]
	v_pk_mul_f32 v[250:251], v[74:75], v[42:43]
	v_pk_mul_f32 v[216:217], v[68:69], v[36:37]
	v_pk_mul_f32 v[218:219], v[70:71], v[38:39]
	v_pk_mul_f32 v[220:221], v[76:77], v[32:33]
	v_pk_mul_f32 v[222:223], v[78:79], v[34:35]
	v_cvt_pk_bf16_f32 v244, v244, v245
	v_cvt_pk_bf16_f32 v245, v246, v247
	v_cvt_pk_bf16_f32 v246, v248, v249
	v_cvt_pk_bf16_f32 v247, v250, v251
	global_store_dwordx4 v208, v[244:247], s[42:43]
	v_cvt_pk_bf16_f32 v216, v216, v217
	v_cvt_pk_bf16_f32 v217, v218, v219
	v_cvt_pk_bf16_f32 v218, v220, v221
	v_cvt_pk_bf16_f32 v219, v222, v223
	global_store_dwordx4 v208, v[216:219], s[42:43] offset:256
; DI u32x4 pack8(const float* v) { u32x4 w; w.x = pk2(v[0], v[1]); w.y = pk2(v[2], v[3]); w.z = pk2(v[4], v[5]); w.w = pk2(v[6], v[7]); return w; }
; #define xor16_32(s) xor16_32_l((s), fr + 16 * fq)
;     DI void operator()(AccRef acc, const Unit& u, int wr, int wc, int fr, int fq) const {
;     ...
;             for (int m = 0; m < 4; ++m) {
;                 const int row = rb + 16 * m;
;                 const float* xi = row < MP ? xin_p + (size_t)row * 1024 : xin_s + (size_t)(row - MP) * 1024;
;                 float s = 0.f;
; #pragma unroll
;                 for (int bj = 0; bj < 2; ++bj) {
;                     const int c = u.pn * 256 + bj * 128 + cl;
;                     float v[8];
; #pragma unroll
;                     for (int n = 0; n < 2; ++n) {
;                         const f32x4 x = *(const f32x4*)(xi + c + 4 * n);
;                         const f32x4 y = x + gt[bj][n] * acc[ai][bj][m][n];
;                         *(f32x4*)(xout + (size_t)row * 1024 + c + 4 * n) = y;
; #pragma unroll
;                         for (int j = 0; j < 4; ++j) { s += y[j] * y[j]; v[4 * n + j] = ap ? y[j] * gs[bj][n][j] : 0.f; }
;                     }
;                     if (ap) *(u32x4*)(ap + (size_t)row * 1024 + c) = pack8(v);
;                 }
;                 s = xor16_32(s);
;                 if (fq == 0) ssq[(size_t)row * 16 + u.pn * 4 + wc] = s;
;             }
.Lnoap_C_6:
	ds_bpermute_b32 v211, v214, v210
	v_permlane16_swap_b32_e32 v44, v40
	v_permlane16_swap_b32_e32 v45, v41
	v_permlane16_swap_b32_e32 v46, v42
	v_permlane16_swap_b32_e32 v47, v43
	v_permlane16_swap_b32_e32 v36, v32
	v_permlane16_swap_b32_e32 v37, v33
	v_permlane16_swap_b32_e32 v38, v34
	v_permlane16_swap_b32_e32 v39, v35
	v_permlane32_swap_b32_e32 v44, v40
	v_permlane32_swap_b32_e32 v45, v41
	v_permlane32_swap_b32_e32 v46, v42
	v_permlane32_swap_b32_e32 v47, v43
	v_permlane32_swap_b32_e32 v36, v32
	v_permlane32_swap_b32_e32 v37, v33
	v_permlane32_swap_b32_e32 v38, v34
	v_permlane32_swap_b32_e32 v39, v35
	global_store_dwordx4 v207, v[44:47], s[8:9]
	global_store_dwordx4 v207, v[40:43], s[8:9] offset:64
	global_store_dwordx4 v207, v[36:39], s[8:9] offset:512
	global_store_dwordx4 v207, v[32:35], s[8:9] offset:576
	v_add_u32_e32 v207, 0x10000, v207
	v_add_u32_e32 v206, 0x10000, v206
	global_load_dwordx4 v[248:251], v206, s[70:71] offset:64
	global_load_dwordx4 v[220:223], v206, s[70:71] offset:576
	global_load_dwordx4 v[244:247], v206, s[70:71]
	global_load_dwordx4 v[216:219], v206, s[70:71] offset:512
	s_waitcnt lgkmcnt(0)
	v_add_f32_e32 v211, v210, v211
	ds_bpermute_b32 v212, v215, v211
	v_add_u32_e32 v208, 0x8000, v208
	s_waitcnt lgkmcnt(0)
	v_add_f32_e32 v211, v211, v212
	s_mov_b64 exec, 0xffff
	global_store_dword v209, v211, s[72:73]
	s_mov_b64 exec, -1
	v_add_u32_e32 v209, 0x400, v209
	s_waitcnt vmcnt(10)
	v_permlane32_swap_b32_e32 v228, v232
	v_permlane32_swap_b32_e32 v229, v233
	v_permlane32_swap_b32_e32 v230, v234
	v_permlane32_swap_b32_e32 v231, v235
	v_permlane32_swap_b32_e32 v236, v240
	v_permlane32_swap_b32_e32 v237, v241
	v_permlane32_swap_b32_e32 v238, v242
	v_permlane32_swap_b32_e32 v239, v243
	v_permlane16_swap_b32_e32 v228, v232
	v_permlane16_swap_b32_e32 v229, v233
	v_permlane16_swap_b32_e32 v230, v234
	v_permlane16_swap_b32_e32 v231, v235
	v_permlane16_swap_b32_e32 v236, v240
	v_permlane16_swap_b32_e32 v237, v241
	v_permlane16_swap_b32_e32 v238, v242
	v_permlane16_swap_b32_e32 v239, v243
	v_pk_fma_f32 v[28:29], v[28:29], v[80:81], v[228:229]
	v_pk_fma_f32 v[30:31], v[30:31], v[82:83], v[230:231]
	v_mul_f32_e32 v210, v29, v29
	v_fmac_f32_e32 v210, v28, v28
	v_fmac_f32_e32 v210, v30, v30
	v_fmac_f32_e32 v210, v31, v31
	v_pk_fma_f32 v[24:25], v[24:25], v[88:89], v[232:233]
	v_pk_fma_f32 v[26:27], v[26:27], v[90:91], v[234:235]
	v_fmac_f32_e32 v210, v24, v24
	v_fmac_f32_e32 v210, v25, v25
	v_fmac_f32_e32 v210, v26, v26
	v_fmac_f32_e32 v210, v27, v27
	v_pk_fma_f32 v[20:21], v[20:21], v[84:85], v[236:237]
	v_pk_fma_f32 v[22:23], v[22:23], v[86:87], v[238:239]
	v_fmac_f32_e32 v210, v20, v20
	v_fmac_f32_e32 v210, v21, v21
	v_fmac_f32_e32 v210, v22, v22
	v_fmac_f32_e32 v210, v23, v23
	v_pk_fma_f32 v[16:17], v[16:17], v[92:93], v[240:241]
	v_pk_fma_f32 v[18:19], v[18:19], v[94:95], v[242:243]
	v_fmac_f32_e32 v210, v16, v16
	v_fmac_f32_e32 v210, v17, v17
	v_fmac_f32_e32 v210, v18, v18
	v_fmac_f32_e32 v210, v19, v19
	s_cmp_lg_u64 s[2:3], 0
	s_cbranch_scc1 .Lnoap_C_7
	v_pk_mul_f32 v[228:229], v[64:65], v[28:29]
	v_pk_mul_f32 v[230:231], v[66:67], v[30:31]
	v_pk_mul_f32 v[232:233], v[72:73], v[24:25]
	v_pk_mul_f32 v[234:235], v[74:75], v[26:27]
	v_pk_mul_f32 v[236:237], v[68:69], v[20:21]
	v_pk_mul_f32 v[238:239], v[70:71], v[22:23]
	v_pk_mul_f32 v[240:241], v[76:77], v[16:17]
	v_pk_mul_f32 v[242:243], v[78:79], v[18:19]
	v_cvt_pk_bf16_f32 v228, v228, v229
	v_cvt_pk_bf16_f32 v229, v230, v231
	v_cvt_pk_bf16_f32 v230, v232, v233
	v_cvt_pk_bf16_f32 v231, v234, v235
	global_store_dwordx4 v208, v[228:231], s[42:43]
	v_cvt_pk_bf16_f32 v236, v236, v237
	v_cvt_pk_bf16_f32 v237, v238, v239
	v_cvt_pk_bf16_f32 v238, v240, v241
	v_cvt_pk_bf16_f32 v239, v242, v243
	global_store_dwordx4 v208, v[236:239], s[42:43] offset:256
; DI u32x4 pack8(const float* v) { u32x4 w; w.x = pk2(v[0], v[1]); w.y = pk2(v[2], v[3]); w.z = pk2(v[4], v[5]); w.w = pk2(v[6], v[7]); return w; }
; #define xor16_32(s) xor16_32_l((s), fr + 16 * fq)
;     DI void operator()(AccRef acc, const Unit& u, int wr, int wc, int fr, int fq) const {
;     ...
;             for (int m = 0; m < 4; ++m) {
;                 const int row = rb + 16 * m;
;                 const float* xi = row < MP ? xin_p + (size_t)row * 1024 : xin_s + (size_t)(row - MP) * 1024;
;                 float s = 0.f;
; #pragma unroll
;                 for (int bj = 0; bj < 2; ++bj) {
;                     const int c = u.pn * 256 + bj * 128 + cl;
;                     float v[8];
; #pragma unroll
;                     for (int n = 0; n < 2; ++n) {
;                         const f32x4 x = *(const f32x4*)(xi + c + 4 * n);
;                         const f32x4 y = x + gt[bj][n] * acc[ai][bj][m][n];
;                         *(f32x4*)(xout + (size_t)row * 1024 + c + 4 * n) = y;
; #pragma unroll
;                         for (int j = 0; j < 4; ++j) { s += y[j] * y[j]; v[4 * n + j] = ap ? y[j] * gs[bj][n][j] : 0.f; }
;                     }
;                     if (ap) *(u32x4*)(ap + (size_t)row * 1024 + c) = pack8(v);
;                 }
;                 s = xor16_32(s);
;                 if (fq == 0) ssq[(size_t)row * 16 + u.pn * 4 + wc] = s;
;             }
.Lnoap_C_7:
	ds_bpermute_b32 v211, v214, v210
	v_permlane16_swap_b32_e32 v28, v24
	v_permlane16_swap_b32_e32 v29, v25
	v_permlane16_swap_b32_e32 v30, v26
	v_permlane16_swap_b32_e32 v31, v27
	v_permlane16_swap_b32_e32 v20, v16
	v_permlane16_swap_b32_e32 v21, v17
	v_permlane16_swap_b32_e32 v22, v18
	v_permlane16_swap_b32_e32 v23, v19
	v_permlane32_swap_b32_e32 v28, v24
	v_permlane32_swap_b32_e32 v29, v25
	v_permlane32_swap_b32_e32 v30, v26
	v_permlane32_swap_b32_e32 v31, v27
	v_permlane32_swap_b32_e32 v20, v16
	v_permlane32_swap_b32_e32 v21, v17
	v_permlane32_swap_b32_e32 v22, v18
	v_permlane32_swap_b32_e32 v23, v19
	global_store_dwordx4 v207, v[28:31], s[8:9]
	global_store_dwordx4 v207, v[24:27], s[8:9] offset:64
	global_store_dwordx4 v207, v[20:23], s[8:9] offset:512
	global_store_dwordx4 v207, v[16:19], s[8:9] offset:576
	v_add_u32_e32 v207, 0x10000, v207
	s_waitcnt lgkmcnt(0)
	v_add_f32_e32 v211, v210, v211
	ds_bpermute_b32 v212, v215, v211
	v_add_u32_e32 v208, 0x8000, v208
	s_waitcnt lgkmcnt(0)
	v_add_f32_e32 v211, v211, v212
	s_mov_b64 exec, 0xffff
	global_store_dword v209, v211, s[72:73]
	s_mov_b64 exec, -1
	v_add_u32_e32 v209, 0x400, v209
	s_waitcnt vmcnt(6)
	v_permlane32_swap_b32_e32 v244, v248
	v_permlane32_swap_b32_e32 v245, v249
	v_permlane32_swap_b32_e32 v246, v250
	v_permlane32_swap_b32_e32 v247, v251
	v_permlane32_swap_b32_e32 v216, v220
	v_permlane32_swap_b32_e32 v217, v221
	v_permlane32_swap_b32_e32 v218, v222
	v_permlane32_swap_b32_e32 v219, v223
	v_permlane16_swap_b32_e32 v244, v248
	v_permlane16_swap_b32_e32 v245, v249
	v_permlane16_swap_b32_e32 v246, v250
	v_permlane16_swap_b32_e32 v247, v251
	v_permlane16_swap_b32_e32 v216, v220
	v_permlane16_swap_b32_e32 v217, v221
	v_permlane16_swap_b32_e32 v218, v222
	v_permlane16_swap_b32_e32 v219, v223
	v_pk_fma_f32 v[12:13], v[12:13], v[80:81], v[244:245]
	v_pk_fma_f32 v[14:15], v[14:15], v[82:83], v[246:247]
	v_mul_f32_e32 v210, v13, v13
	v_fmac_f32_e32 v210, v12, v12
	v_fmac_f32_e32 v210, v14, v14
	v_fmac_f32_e32 v210, v15, v15
	v_pk_fma_f32 v[8:9], v[8:9], v[88:89], v[248:249]
	v_pk_fma_f32 v[10:11], v[10:11], v[90:91], v[250:251]
	v_fmac_f32_e32 v210, v8, v8
	v_fmac_f32_e32 v210, v9, v9
	v_fmac_f32_e32 v210, v10, v10
	v_fmac_f32_e32 v210, v11, v11
	v_pk_fma_f32 v[4:5], v[4:5], v[84:85], v[216:217]
	v_pk_fma_f32 v[6:7], v[6:7], v[86:87], v[218:219]
	v_fmac_f32_e32 v210, v4, v4
	v_fmac_f32_e32 v210, v5, v5
	v_fmac_f32_e32 v210, v6, v6
	v_fmac_f32_e32 v210, v7, v7
	v_pk_fma_f32 v[0:1], v[0:1], v[92:93], v[220:221]
	v_pk_fma_f32 v[2:3], v[2:3], v[94:95], v[222:223]
	v_fmac_f32_e32 v210, v0, v0
	v_fmac_f32_e32 v210, v1, v1
	v_fmac_f32_e32 v210, v2, v2
	v_fmac_f32_e32 v210, v3, v3
	s_cmp_lg_u64 s[2:3], 0
	s_cbranch_scc1 .Lnoap_C_8
	v_pk_mul_f32 v[244:245], v[64:65], v[12:13]
	v_pk_mul_f32 v[246:247], v[66:67], v[14:15]
	v_pk_mul_f32 v[248:249], v[72:73], v[8:9]
	v_pk_mul_f32 v[250:251], v[74:75], v[10:11]
	v_pk_mul_f32 v[216:217], v[68:69], v[4:5]
	v_pk_mul_f32 v[218:219], v[70:71], v[6:7]
	v_pk_mul_f32 v[220:221], v[76:77], v[0:1]
	v_pk_mul_f32 v[222:223], v[78:79], v[2:3]
	v_cvt_pk_bf16_f32 v244, v244, v245
	v_cvt_pk_bf16_f32 v245, v246, v247
	v_cvt_pk_bf16_f32 v246, v248, v249
	v_cvt_pk_bf16_f32 v247, v250, v251
	global_store_dwordx4 v208, v[244:247], s[42:43]
	v_cvt_pk_bf16_f32 v216, v216, v217
	v_cvt_pk_bf16_f32 v217, v218, v219
	v_cvt_pk_bf16_f32 v218, v220, v221
	v_cvt_pk_bf16_f32 v219, v222, v223
	global_store_dwordx4 v208, v[216:219], s[42:43] offset:256
.Lnoap_C_8:
	ds_bpermute_b32 v211, v214, v210
	v_permlane16_swap_b32_e32 v12, v8
	v_permlane16_swap_b32_e32 v13, v9
	v_permlane16_swap_b32_e32 v14, v10
	v_permlane16_swap_b32_e32 v15, v11
	v_permlane16_swap_b32_e32 v4, v0
	v_permlane16_swap_b32_e32 v5, v1
	v_permlane16_swap_b32_e32 v6, v2
	v_permlane16_swap_b32_e32 v7, v3
	v_permlane32_swap_b32_e32 v12, v8
	v_permlane32_swap_b32_e32 v13, v9
	v_permlane32_swap_b32_e32 v14, v10
	v_permlane32_swap_b32_e32 v15, v11
	v_permlane32_swap_b32_e32 v4, v0
	v_permlane32_swap_b32_e32 v5, v1
	v_permlane32_swap_b32_e32 v6, v2
	v_permlane32_swap_b32_e32 v7, v3
	global_store_dwordx4 v207, v[12:15], s[8:9]
	global_store_dwordx4 v207, v[8:11], s[8:9] offset:64
	global_store_dwordx4 v207, v[4:7], s[8:9] offset:512
	global_store_dwordx4 v207, v[0:3], s[8:9] offset:576
	s_waitcnt lgkmcnt(0)
	v_add_f32_e32 v211, v210, v211
	ds_bpermute_b32 v212, v215, v211
	s_waitcnt lgkmcnt(0)
	v_add_f32_e32 v211, v211, v212
	s_mov_b64 exec, 0xffff
	global_store_dword v209, v211, s[72:73]
	s_mov_b64 exec, -1
	s_and_b64 vcc, exec, s[0:1]
	s_mov_b64 s[0:1], -1
	s_cbranch_vccnz .LBB0_1500
	s_andn2_b64 vcc, exec, s[16:17]
	s_cbranch_vccnz .LBB0_1499
	s_barrier
	s_branch .LBB0_1499

; DI u32x4 pack8(const float* v) { u32x4 w; w.x = pk2(v[0], v[1]); w.y = pk2(v[2], v[3]); w.z = pk2(v[4], v[5]); w.w = pk2(v[6], v[7]); return w; }
; #define xor16_32(s) xor16_32_l((s), fr + 16 * fq)
;     DI void operator()(AccRef acc, const Unit& u, int wr, int wc, int fr, int fq) const {
;         const int cl = wc * 32 + fq * 8;
;         const float* gate = (const float*)(ws + WS_MOD) + gate_off; const float* scn = (const float*)(ws + WS_MOD) + scn_off;
;         bf16_t* ap = has_ap ? (bf16_t*)(ws + WS_U + U_AP) : nullptr; float* ssq = (float*)(ws + WS_SSQ);
; #pragma unroll
;         for (int ai = 0; ai < 2; ++ai) {
;             const int rb = u.pm * 256 + ai * 128 + wr * 64 + fr;
;             int mb, pos0, kv0; row_info(rb, mb, pos0, kv0);
;             f32x4 gt[2][2], gs[2][2];
; #pragma unroll
;             for (int bj = 0; bj < 2; ++bj)
; #pragma unroll
;                 for (int n = 0; n < 2; ++n) {
;                     const int c = u.pn * 256 + bj * 128 + cl + 4 * n;
;                     gt[bj][n] = *(const f32x4*)(gate + (size_t)mb * 6144 + c);
;                     if (ap) { const f32x4 g = *(const f32x4*)(gn + c), s = *(const f32x4*)(scn + (size_t)mb * 6144 + c); gs[bj][n] = g * (s + 1.f); }
;                 }
; #pragma unroll
;             for (int m = 0; m < 4; ++m) {
;                 const int row = rb + 16 * m;
;                 const float* xi = row < MP ? xin_p + (size_t)row * 1024 : xin_s + (size_t)(row - MP) * 1024;
;                 float s = 0.f;
; #pragma unroll
;                 for (int bj = 0; bj < 2; ++bj) {
;                     const int c = u.pn * 256 + bj * 128 + cl;
;                     float v[8];
; #pragma unroll
;                     for (int n = 0; n < 2; ++n) {
;                         const f32x4 x = *(const f32x4*)(xi + c + 4 * n);
;                         const f32x4 y = x + gt[bj][n] * acc[ai][bj][m][n];
;                         *(f32x4*)(xout + (size_t)row * 1024 + c + 4 * n) = y;
; #pragma unroll
;                         for (int j = 0; j < 4; ++j) { s += y[j] * y[j]; v[4 * n + j] = ap ? y[j] * gs[bj][n][j] : 0.f; }
;                     }
;                     if (ap) *(u32x4*)(ap + (size_t)row * 1024 + c) = pack8(v);
;                 }
;                 s = xor16_32(s);
;                 if (fq == 0) ssq[(size_t)row * 16 + u.pn * 4 + wc] = s;
;             }
.LBB0_2061:
	s_or_b64 exec, exec, s[4:5]
	s_sub_u32 s70, s10, 0x4000000
	s_subb_u32 s71, s11, 0
	s_cmp_ge_u32 s43, 64
	s_cselect_b32 s70, s70, s84
	s_cselect_b32 s71, s71, s85
	s_lshl_b32 s14, s42, 4
	s_add_u32 s72, s52, s14
	s_addc_u32 s73, s53, 0
	s_lshl_b32 s14, s54, 2
	s_add_u32 s72, s72, s14
	s_addc_u32 s73, s73, 0
	v_lshlrev_b32_e32 v213, 2, v172
	v_lshl_add_u32 v206, v176, 12, v213
	v_lshlrev_b32_e32 v213, 4, v194
	v_sub_u32_e32 v206, v206, v213
	v_mov_b32_e32 v207, v206
	v_lshlrev_b32_e32 v213, 11, v176
	v_lshl_add_u32 v208, v172, 1, v213
	v_lshlrev_b32_e32 v209, 6, v176
	v_lshlrev_b32_e32 v213, 2, v195
	v_lshl_add_u32 v213, v194, 6, v213
	v_xor_b32_e32 v214, 64, v213
	v_xor_b32_e32 v215, 0x80, v213
	global_load_dwordx4 v[232:235], v206, s[70:71] offset:64
	global_load_dwordx4 v[240:243], v206, s[70:71] offset:576
	global_load_dwordx4 v[228:231], v206, s[70:71]
	global_load_dwordx4 v[236:239], v206, s[70:71] offset:512
	v_add_u32_e32 v206, 0x10000, v206
	global_load_dwordx4 v[248:251], v206, s[70:71] offset:64
	global_load_dwordx4 v[220:223], v206, s[70:71] offset:576
	global_load_dwordx4 v[244:247], v206, s[70:71]
	global_load_dwordx4 v[216:219], v206, s[70:71] offset:512
	v_add_u32_e32 v206, 0x10000, v206
	s_waitcnt vmcnt(4)
	v_permlane32_swap_b32_e32 v228, v232
	v_permlane32_swap_b32_e32 v229, v233
	v_permlane32_swap_b32_e32 v230, v234
	v_permlane32_swap_b32_e32 v231, v235
	v_permlane32_swap_b32_e32 v236, v240
	v_permlane32_swap_b32_e32 v237, v241
	v_permlane32_swap_b32_e32 v238, v242
	v_permlane32_swap_b32_e32 v239, v243
	v_permlane16_swap_b32_e32 v228, v232
	v_permlane16_swap_b32_e32 v229, v233
	v_permlane16_swap_b32_e32 v230, v234
	v_permlane16_swap_b32_e32 v231, v235
	v_permlane16_swap_b32_e32 v236, v240
	v_permlane16_swap_b32_e32 v237, v241
	v_permlane16_swap_b32_e32 v238, v242
	v_permlane16_swap_b32_e32 v239, v243
	v_pk_fma_f32 v[140:141], v[140:141], v[144:145], v[228:229]
	v_pk_fma_f32 v[142:143], v[142:143], v[146:147], v[230:231]
	v_mul_f32_e32 v210, v141, v141
	v_fmac_f32_e32 v210, v140, v140
	v_fmac_f32_e32 v210, v142, v142
	v_fmac_f32_e32 v210, v143, v143
	v_pk_fma_f32 v[136:137], v[136:137], v[152:153], v[232:233]
	v_pk_fma_f32 v[138:139], v[138:139], v[154:155], v[234:235]
	v_fmac_f32_e32 v210, v136, v136
	v_fmac_f32_e32 v210, v137, v137
	v_fmac_f32_e32 v210, v138, v138
	v_fmac_f32_e32 v210, v139, v139
	v_pk_fma_f32 v[132:133], v[132:133], v[148:149], v[236:237]
	v_pk_fma_f32 v[134:135], v[134:135], v[150:151], v[238:239]
	v_fmac_f32_e32 v210, v132, v132
	v_fmac_f32_e32 v210, v133, v133
	v_fmac_f32_e32 v210, v134, v134
	v_fmac_f32_e32 v210, v135, v135
	v_pk_fma_f32 v[128:129], v[128:129], v[156:157], v[240:241]
	v_pk_fma_f32 v[130:131], v[130:131], v[158:159], v[242:243]
	v_fmac_f32_e32 v210, v128, v128
	v_fmac_f32_e32 v210, v129, v129
	v_fmac_f32_e32 v210, v130, v130
	v_fmac_f32_e32 v210, v131, v131
	s_cmp_lg_u64 s[0:1], 0
	s_cbranch_scc1 .Lnoap_D_1
	v_pk_mul_f32 v[228:229], v[64:65], v[140:141]
	v_pk_mul_f32 v[230:231], v[66:67], v[142:143]
	v_pk_mul_f32 v[232:233], v[72:73], v[136:137]
	v_pk_mul_f32 v[234:235], v[74:75], v[138:139]
	v_pk_mul_f32 v[236:237], v[68:69], v[132:133]
	v_pk_mul_f32 v[238:239], v[70:71], v[134:135]
	v_pk_mul_f32 v[240:241], v[76:77], v[128:129]
	v_pk_mul_f32 v[242:243], v[78:79], v[130:131]
	v_cvt_pk_bf16_f32 v228, v228, v229
	v_cvt_pk_bf16_f32 v229, v230, v231
	v_cvt_pk_bf16_f32 v230, v232, v233
	v_cvt_pk_bf16_f32 v231, v234, v235
	global_store_dwordx4 v208, v[228:231], s[28:29]
	v_cvt_pk_bf16_f32 v236, v236, v237
	v_cvt_pk_bf16_f32 v237, v238, v239
	v_cvt_pk_bf16_f32 v238, v240, v241
	v_cvt_pk_bf16_f32 v239, v242, v243
	global_store_dwordx4 v208, v[236:239], s[28:29] offset:256
.Lnoap_D_1:
	ds_bpermute_b32 v211, v214, v210
	v_permlane16_swap_b32_e32 v140, v136
	v_permlane16_swap_b32_e32 v141, v137
	v_permlane16_swap_b32_e32 v142, v138
	v_permlane16_swap_b32_e32 v143, v139
	v_permlane16_swap_b32_e32 v132, v128
	v_permlane16_swap_b32_e32 v133, v129
	v_permlane16_swap_b32_e32 v134, v130
	v_permlane16_swap_b32_e32 v135, v131
	v_permlane32_swap_b32_e32 v140, v136
	v_permlane32_swap_b32_e32 v141, v137
	v_permlane32_swap_b32_e32 v142, v138
	v_permlane32_swap_b32_e32 v143, v139
	v_permlane32_swap_b32_e32 v132, v128
	v_permlane32_swap_b32_e32 v133, v129
	v_permlane32_swap_b32_e32 v134, v130
	v_permlane32_swap_b32_e32 v135, v131
	global_store_dwordx4 v207, v[140:143], s[84:85]
	global_store_dwordx4 v207, v[136:139], s[84:85] offset:64
	global_store_dwordx4 v207, v[132:135], s[84:85] offset:512
	global_store_dwordx4 v207, v[128:131], s[84:85] offset:576
	v_add_u32_e32 v207, 0x10000, v207
	global_load_dwordx4 v[232:235], v206, s[70:71] offset:64
	global_load_dwordx4 v[240:243], v206, s[70:71] offset:576
	global_load_dwordx4 v[228:231], v206, s[70:71]
	global_load_dwordx4 v[236:239], v206, s[70:71] offset:512
	s_waitcnt lgkmcnt(0)
	v_add_f32_e32 v211, v210, v211
	ds_bpermute_b32 v212, v215, v211
	v_add_u32_e32 v208, 0x8000, v208
	s_waitcnt lgkmcnt(0)
	v_add_f32_e32 v211, v211, v212
	s_mov_b64 exec, 0xffff
	global_store_dword v209, v211, s[72:73]
	s_mov_b64 exec, -1
	v_add_u32_e32 v209, 0x400, v209
	s_waitcnt vmcnt(9)
	v_permlane32_swap_b32_e32 v244, v248
	v_permlane32_swap_b32_e32 v245, v249
	v_permlane32_swap_b32_e32 v246, v250
	v_permlane32_swap_b32_e32 v247, v251
	v_permlane32_swap_b32_e32 v216, v220
	v_permlane32_swap_b32_e32 v217, v221
	v_permlane32_swap_b32_e32 v218, v222
	v_permlane32_swap_b32_e32 v219, v223
	v_permlane16_swap_b32_e32 v244, v248
	v_permlane16_swap_b32_e32 v245, v249
	v_permlane16_swap_b32_e32 v246, v250
	v_permlane16_swap_b32_e32 v247, v251
	v_permlane16_swap_b32_e32 v216, v220
	v_permlane16_swap_b32_e32 v217, v221
	v_permlane16_swap_b32_e32 v218, v222
	v_permlane16_swap_b32_e32 v219, v223
	v_pk_fma_f32 v[124:125], v[124:125], v[144:145], v[244:245]
	v_pk_fma_f32 v[126:127], v[126:127], v[146:147], v[246:247]
	v_mul_f32_e32 v210, v125, v125
	v_fmac_f32_e32 v210, v124, v124
	v_fmac_f32_e32 v210, v126, v126
	v_fmac_f32_e32 v210, v127, v127
	v_pk_fma_f32 v[120:121], v[120:121], v[152:153], v[248:249]
	v_pk_fma_f32 v[122:123], v[122:123], v[154:155], v[250:251]
	v_fmac_f32_e32 v210, v120, v120
	v_fmac_f32_e32 v210, v121, v121
	v_fmac_f32_e32 v210, v122, v122
	v_fmac_f32_e32 v210, v123, v123
	v_pk_fma_f32 v[116:117], v[116:117], v[148:149], v[216:217]
	v_pk_fma_f32 v[118:119], v[118:119], v[150:151], v[218:219]
	v_fmac_f32_e32 v210, v116, v116
	v_fmac_f32_e32 v210, v117, v117
	v_fmac_f32_e32 v210, v118, v118
	v_fmac_f32_e32 v210, v119, v119
	v_pk_fma_f32 v[112:113], v[112:113], v[156:157], v[220:221]
	v_pk_fma_f32 v[114:115], v[114:115], v[158:159], v[222:223]
	v_fmac_f32_e32 v210, v112, v112
	v_fmac_f32_e32 v210, v113, v113
	v_fmac_f32_e32 v210, v114, v114
	v_fmac_f32_e32 v210, v115, v115
	s_cmp_lg_u64 s[0:1], 0
	s_cbranch_scc1 .Lnoap_D_2
; DI u32x4 pack8(const float* v) { u32x4 w; w.x = pk2(v[0], v[1]); w.y = pk2(v[2], v[3]); w.z = pk2(v[4], v[5]); w.w = pk2(v[6], v[7]); return w; }
; #define xor16_32(s) xor16_32_l((s), fr + 16 * fq)
;     DI void operator()(AccRef acc, const Unit& u, int wr, int wc, int fr, int fq) const {
;     ...
;             for (int m = 0; m < 4; ++m) {
;                 const int row = rb + 16 * m;
;                 const float* xi = row < MP ? xin_p + (size_t)row * 1024 : xin_s + (size_t)(row - MP) * 1024;
;                 float s = 0.f;
; #pragma unroll
;                 for (int bj = 0; bj < 2; ++bj) {
;                     const int c = u.pn * 256 + bj * 128 + cl;
;                     float v[8];
; #pragma unroll
;                     for (int n = 0; n < 2; ++n) {
;                         const f32x4 x = *(const f32x4*)(xi + c + 4 * n);
;                         const f32x4 y = x + gt[bj][n] * acc[ai][bj][m][n];
;                         *(f32x4*)(xout + (size_t)row * 1024 + c + 4 * n) = y;
; #pragma unroll
;                         for (int j = 0; j < 4; ++j) { s += y[j] * y[j]; v[4 * n + j] = ap ? y[j] * gs[bj][n][j] : 0.f; }
;                     }
;                     if (ap) *(u32x4*)(ap + (size_t)row * 1024 + c) = pack8(v);
;                 }
;                 s = xor16_32(s);
;                 if (fq == 0) ssq[(size_t)row * 16 + u.pn * 4 + wc] = s;
;             }
	v_pk_mul_f32 v[244:245], v[64:65], v[124:125]
	v_pk_mul_f32 v[246:247], v[66:67], v[126:127]
	v_pk_mul_f32 v[248:249], v[72:73], v[120:121]
	v_pk_mul_f32 v[250:251], v[74:75], v[122:123]
	v_pk_mul_f32 v[216:217], v[68:69], v[116:117]
	v_pk_mul_f32 v[218:219], v[70:71], v[118:119]
	v_pk_mul_f32 v[220:221], v[76:77], v[112:113]
	v_pk_mul_f32 v[222:223], v[78:79], v[114:115]
	v_cvt_pk_bf16_f32 v244, v244, v245
	v_cvt_pk_bf16_f32 v245, v246, v247
	v_cvt_pk_bf16_f32 v246, v248, v249
	v_cvt_pk_bf16_f32 v247, v250, v251
	global_store_dwordx4 v208, v[244:247], s[28:29]
	v_cvt_pk_bf16_f32 v216, v216, v217
	v_cvt_pk_bf16_f32 v217, v218, v219
	v_cvt_pk_bf16_f32 v218, v220, v221
	v_cvt_pk_bf16_f32 v219, v222, v223
	global_store_dwordx4 v208, v[216:219], s[28:29] offset:256
.Lnoap_D_2:
	ds_bpermute_b32 v211, v214, v210
	v_permlane16_swap_b32_e32 v124, v120
	v_permlane16_swap_b32_e32 v125, v121
	v_permlane16_swap_b32_e32 v126, v122
	v_permlane16_swap_b32_e32 v127, v123
	v_permlane16_swap_b32_e32 v116, v112
	v_permlane16_swap_b32_e32 v117, v113
	v_permlane16_swap_b32_e32 v118, v114
	v_permlane16_swap_b32_e32 v119, v115
	v_permlane32_swap_b32_e32 v124, v120
	v_permlane32_swap_b32_e32 v125, v121
	v_permlane32_swap_b32_e32 v126, v122
	v_permlane32_swap_b32_e32 v127, v123
	v_permlane32_swap_b32_e32 v116, v112
	v_permlane32_swap_b32_e32 v117, v113
	v_permlane32_swap_b32_e32 v118, v114
	v_permlane32_swap_b32_e32 v119, v115
	global_store_dwordx4 v207, v[124:127], s[84:85]
	global_store_dwordx4 v207, v[120:123], s[84:85] offset:64
	global_store_dwordx4 v207, v[116:119], s[84:85] offset:512
	global_store_dwordx4 v207, v[112:115], s[84:85] offset:576
	v_add_u32_e32 v207, 0x10000, v207
	v_add_u32_e32 v206, 0x10000, v206
	global_load_dwordx4 v[248:251], v206, s[70:71] offset:64
	global_load_dwordx4 v[220:223], v206, s[70:71] offset:576
	global_load_dwordx4 v[244:247], v206, s[70:71]
	global_load_dwordx4 v[216:219], v206, s[70:71] offset:512
	s_waitcnt lgkmcnt(0)
	v_add_f32_e32 v211, v210, v211
	ds_bpermute_b32 v212, v215, v211
	v_add_u32_e32 v208, 0x8000, v208
	s_waitcnt lgkmcnt(0)
	v_add_f32_e32 v211, v211, v212
	s_mov_b64 exec, 0xffff
	global_store_dword v209, v211, s[72:73]
	s_mov_b64 exec, -1
	v_add_u32_e32 v209, 0x400, v209
	s_waitcnt vmcnt(10)
	v_permlane32_swap_b32_e32 v228, v232
	v_permlane32_swap_b32_e32 v229, v233
	v_permlane32_swap_b32_e32 v230, v234
	v_permlane32_swap_b32_e32 v231, v235
	v_permlane32_swap_b32_e32 v236, v240
	v_permlane32_swap_b32_e32 v237, v241
	v_permlane32_swap_b32_e32 v238, v242
	v_permlane32_swap_b32_e32 v239, v243
	v_permlane16_swap_b32_e32 v228, v232
	v_permlane16_swap_b32_e32 v229, v233
	v_permlane16_swap_b32_e32 v230, v234
	v_permlane16_swap_b32_e32 v231, v235
	v_permlane16_swap_b32_e32 v236, v240
	v_permlane16_swap_b32_e32 v237, v241
	v_permlane16_swap_b32_e32 v238, v242
	v_permlane16_swap_b32_e32 v239, v243
	v_pk_fma_f32 v[108:109], v[108:109], v[144:145], v[228:229]
	v_pk_fma_f32 v[110:111], v[110:111], v[146:147], v[230:231]
	v_mul_f32_e32 v210, v109, v109
	v_fmac_f32_e32 v210, v108, v108
	v_fmac_f32_e32 v210, v110, v110
	v_fmac_f32_e32 v210, v111, v111
	v_pk_fma_f32 v[104:105], v[104:105], v[152:153], v[232:233]
	v_pk_fma_f32 v[106:107], v[106:107], v[154:155], v[234:235]
	v_fmac_f32_e32 v210, v104, v104
	v_fmac_f32_e32 v210, v105, v105
	v_fmac_f32_e32 v210, v106, v106
	v_fmac_f32_e32 v210, v107, v107
	v_pk_fma_f32 v[100:101], v[100:101], v[148:149], v[236:237]
	v_pk_fma_f32 v[102:103], v[102:103], v[150:151], v[238:239]
	v_fmac_f32_e32 v210, v100, v100
	v_fmac_f32_e32 v210, v101, v101
	v_fmac_f32_e32 v210, v102, v102
	v_fmac_f32_e32 v210, v103, v103
	v_pk_fma_f32 v[96:97], v[96:97], v[156:157], v[240:241]
	v_pk_fma_f32 v[98:99], v[98:99], v[158:159], v[242:243]
	v_fmac_f32_e32 v210, v96, v96
	v_fmac_f32_e32 v210, v97, v97
	v_fmac_f32_e32 v210, v98, v98
	v_fmac_f32_e32 v210, v99, v99
	s_cmp_lg_u64 s[0:1], 0
	s_cbranch_scc1 .Lnoap_D_3
	v_pk_mul_f32 v[228:229], v[64:65], v[108:109]
	v_pk_mul_f32 v[230:231], v[66:67], v[110:111]
	v_pk_mul_f32 v[232:233], v[72:73], v[104:105]
	v_pk_mul_f32 v[234:235], v[74:75], v[106:107]
	v_pk_mul_f32 v[236:237], v[68:69], v[100:101]
	v_pk_mul_f32 v[238:239], v[70:71], v[102:103]
	v_pk_mul_f32 v[240:241], v[76:77], v[96:97]
	v_pk_mul_f32 v[242:243], v[78:79], v[98:99]
	v_cvt_pk_bf16_f32 v228, v228, v229
	v_cvt_pk_bf16_f32 v229, v230, v231
	v_cvt_pk_bf16_f32 v230, v232, v233
	v_cvt_pk_bf16_f32 v231, v234, v235
	global_store_dwordx4 v208, v[228:231], s[28:29]
	v_cvt_pk_bf16_f32 v236, v236, v237
	v_cvt_pk_bf16_f32 v237, v238, v239
	v_cvt_pk_bf16_f32 v238, v240, v241
	v_cvt_pk_bf16_f32 v239, v242, v243
	global_store_dwordx4 v208, v[236:239], s[28:29] offset:256
; DI u32x4 pack8(const float* v) { u32x4 w; w.x = pk2(v[0], v[1]); w.y = pk2(v[2], v[3]); w.z = pk2(v[4], v[5]); w.w = pk2(v[6], v[7]); return w; }
; #define xor16_32(s) xor16_32_l((s), fr + 16 * fq)
;     DI void operator()(AccRef acc, const Unit& u, int wr, int wc, int fr, int fq) const {
;     ...
; #pragma unroll
;         for (int ai = 0; ai < 2; ++ai) {
;             const int rb = u.pm * 256 + ai * 128 + wr * 64 + fr;
;             int mb, pos0, kv0; row_info(rb, mb, pos0, kv0);
;             f32x4 gt[2][2], gs[2][2];
; #pragma unroll
;             for (int bj = 0; bj < 2; ++bj)
; #pragma unroll
;                 for (int n = 0; n < 2; ++n) {
;                     const int c = u.pn * 256 + bj * 128 + cl + 4 * n;
;                     gt[bj][n] = *(const f32x4*)(gate + (size_t)mb * 6144 + c);
;                     if (ap) { const f32x4 g = *(const f32x4*)(gn + c), s = *(const f32x4*)(scn + (size_t)mb * 6144 + c); gs[bj][n] = g * (s + 1.f); }
;                 }
; #pragma unroll
;             for (int m = 0; m < 4; ++m) {
;                 const int row = rb + 16 * m;
;                 const float* xi = row < MP ? xin_p + (size_t)row * 1024 : xin_s + (size_t)(row - MP) * 1024;
;                 float s = 0.f;
; #pragma unroll
;                 for (int bj = 0; bj < 2; ++bj) {
;                     const int c = u.pn * 256 + bj * 128 + cl;
;                     float v[8];
; #pragma unroll
;                     for (int n = 0; n < 2; ++n) {
;                         const f32x4 x = *(const f32x4*)(xi + c + 4 * n);
;                         const f32x4 y = x + gt[bj][n] * acc[ai][bj][m][n];
;                         *(f32x4*)(xout + (size_t)row * 1024 + c + 4 * n) = y;
; #pragma unroll
;                         for (int j = 0; j < 4; ++j) { s += y[j] * y[j]; v[4 * n + j] = ap ? y[j] * gs[bj][n][j] : 0.f; }
;                     }
;                     if (ap) *(u32x4*)(ap + (size_t)row * 1024 + c) = pack8(v);
;                 }
;                 s = xor16_32(s);
;                 if (fq == 0) ssq[(size_t)row * 16 + u.pn * 4 + wc] = s;
;             }
.Lnoap_D_3:
	ds_bpermute_b32 v211, v214, v210
	v_permlane16_swap_b32_e32 v108, v104
	v_permlane16_swap_b32_e32 v109, v105
	v_permlane16_swap_b32_e32 v110, v106
	v_permlane16_swap_b32_e32 v111, v107
	v_permlane16_swap_b32_e32 v100, v96
	v_permlane16_swap_b32_e32 v101, v97
	v_permlane16_swap_b32_e32 v102, v98
	v_permlane16_swap_b32_e32 v103, v99
	v_permlane32_swap_b32_e32 v108, v104
	v_permlane32_swap_b32_e32 v109, v105
	v_permlane32_swap_b32_e32 v110, v106
	v_permlane32_swap_b32_e32 v111, v107
	v_permlane32_swap_b32_e32 v100, v96
	v_permlane32_swap_b32_e32 v101, v97
	v_permlane32_swap_b32_e32 v102, v98
	v_permlane32_swap_b32_e32 v103, v99
	global_store_dwordx4 v207, v[108:111], s[84:85]
	global_store_dwordx4 v207, v[104:107], s[84:85] offset:64
	global_store_dwordx4 v207, v[100:103], s[84:85] offset:512
	global_store_dwordx4 v207, v[96:99], s[84:85] offset:576
	v_add_u32_e32 v207, 0x10000, v207
	v_add_u32_e32 v206, 0x50000, v206
	global_load_dwordx4 v[232:235], v206, s[70:71] offset:64
	global_load_dwordx4 v[240:243], v206, s[70:71] offset:576
	global_load_dwordx4 v[228:231], v206, s[70:71]
	global_load_dwordx4 v[236:239], v206, s[70:71] offset:512
	s_waitcnt lgkmcnt(0)
	v_add_f32_e32 v211, v210, v211
	ds_bpermute_b32 v212, v215, v211
	v_add_u32_e32 v208, 0x8000, v208
	s_waitcnt lgkmcnt(0)
	v_add_f32_e32 v211, v211, v212
	s_mov_b64 exec, 0xffff
	global_store_dword v209, v211, s[72:73]
	s_mov_b64 exec, -1
	v_add_u32_e32 v209, 0x400, v209
	s_waitcnt vmcnt(10)
	v_permlane32_swap_b32_e32 v244, v248
	v_permlane32_swap_b32_e32 v245, v249
	v_permlane32_swap_b32_e32 v246, v250
	v_permlane32_swap_b32_e32 v247, v251
	v_permlane32_swap_b32_e32 v216, v220
	v_permlane32_swap_b32_e32 v217, v221
	v_permlane32_swap_b32_e32 v218, v222
	v_permlane32_swap_b32_e32 v219, v223
	v_permlane16_swap_b32_e32 v244, v248
	v_permlane16_swap_b32_e32 v245, v249
	v_permlane16_swap_b32_e32 v246, v250
	v_permlane16_swap_b32_e32 v247, v251
	v_permlane16_swap_b32_e32 v216, v220
	v_permlane16_swap_b32_e32 v217, v221
	v_permlane16_swap_b32_e32 v218, v222
	v_permlane16_swap_b32_e32 v219, v223
	v_pk_fma_f32 v[92:93], v[92:93], v[144:145], v[244:245]
	v_pk_fma_f32 v[94:95], v[94:95], v[146:147], v[246:247]
	v_mul_f32_e32 v210, v93, v93
	v_fmac_f32_e32 v210, v92, v92
	v_fmac_f32_e32 v210, v94, v94
	v_fmac_f32_e32 v210, v95, v95
	v_pk_fma_f32 v[88:89], v[88:89], v[152:153], v[248:249]
	v_pk_fma_f32 v[90:91], v[90:91], v[154:155], v[250:251]
	v_fmac_f32_e32 v210, v88, v88
	v_fmac_f32_e32 v210, v89, v89
	v_fmac_f32_e32 v210, v90, v90
	v_fmac_f32_e32 v210, v91, v91
	v_pk_fma_f32 v[84:85], v[84:85], v[148:149], v[216:217]
	v_pk_fma_f32 v[86:87], v[86:87], v[150:151], v[218:219]
	v_fmac_f32_e32 v210, v84, v84
	v_fmac_f32_e32 v210, v85, v85
	v_fmac_f32_e32 v210, v86, v86
	v_fmac_f32_e32 v210, v87, v87
	v_pk_fma_f32 v[80:81], v[80:81], v[156:157], v[220:221]
	v_pk_fma_f32 v[82:83], v[82:83], v[158:159], v[222:223]
	v_fmac_f32_e32 v210, v80, v80
	v_fmac_f32_e32 v210, v81, v81
	v_fmac_f32_e32 v210, v82, v82
	v_fmac_f32_e32 v210, v83, v83
	s_cmp_lg_u64 s[0:1], 0
	s_cbranch_scc1 .Lnoap_D_4
	v_pk_mul_f32 v[244:245], v[64:65], v[92:93]
	v_pk_mul_f32 v[246:247], v[66:67], v[94:95]
	v_pk_mul_f32 v[248:249], v[72:73], v[88:89]
	v_pk_mul_f32 v[250:251], v[74:75], v[90:91]
	v_pk_mul_f32 v[216:217], v[68:69], v[84:85]
	v_pk_mul_f32 v[218:219], v[70:71], v[86:87]
	v_pk_mul_f32 v[220:221], v[76:77], v[80:81]
	v_pk_mul_f32 v[222:223], v[78:79], v[82:83]
	v_cvt_pk_bf16_f32 v244, v244, v245
	v_cvt_pk_bf16_f32 v245, v246, v247
	v_cvt_pk_bf16_f32 v246, v248, v249
	v_cvt_pk_bf16_f32 v247, v250, v251
	global_store_dwordx4 v208, v[244:247], s[28:29]
	v_cvt_pk_bf16_f32 v216, v216, v217
	v_cvt_pk_bf16_f32 v217, v218, v219
	v_cvt_pk_bf16_f32 v218, v220, v221
	v_cvt_pk_bf16_f32 v219, v222, v223
	global_store_dwordx4 v208, v[216:219], s[28:29] offset:256
.Lnoap_D_4:
	ds_bpermute_b32 v211, v214, v210
	v_permlane16_swap_b32_e32 v92, v88
	v_permlane16_swap_b32_e32 v93, v89
	v_permlane16_swap_b32_e32 v94, v90
	v_permlane16_swap_b32_e32 v95, v91
	v_permlane16_swap_b32_e32 v84, v80
	v_permlane16_swap_b32_e32 v85, v81
	v_permlane16_swap_b32_e32 v86, v82
	v_permlane16_swap_b32_e32 v87, v83
	v_permlane32_swap_b32_e32 v92, v88
	v_permlane32_swap_b32_e32 v93, v89
	v_permlane32_swap_b32_e32 v94, v90
	v_permlane32_swap_b32_e32 v95, v91
	v_permlane32_swap_b32_e32 v84, v80
	v_permlane32_swap_b32_e32 v85, v81
	v_permlane32_swap_b32_e32 v86, v82
	v_permlane32_swap_b32_e32 v87, v83
	global_store_dwordx4 v207, v[92:95], s[84:85]
	global_store_dwordx4 v207, v[88:91], s[84:85] offset:64
	global_store_dwordx4 v207, v[84:87], s[84:85] offset:512
	global_store_dwordx4 v207, v[80:83], s[84:85] offset:576
	v_add_u32_e32 v207, 0x50000, v207
	v_add_u32_e32 v206, 0x10000, v206
	global_load_dwordx4 v[248:251], v206, s[70:71] offset:64
	global_load_dwordx4 v[220:223], v206, s[70:71] offset:576
	global_load_dwordx4 v[244:247], v206, s[70:71]
	global_load_dwordx4 v[216:219], v206, s[70:71] offset:512
	s_waitcnt lgkmcnt(0)
	v_add_f32_e32 v211, v210, v211
	ds_bpermute_b32 v212, v215, v211
	v_add_u32_e32 v208, 0x28000, v208
	s_waitcnt lgkmcnt(0)
	v_add_f32_e32 v211, v211, v212
	s_mov_b64 exec, 0xffff
	global_store_dword v209, v211, s[72:73]
	s_mov_b64 exec, -1
	v_add_u32_e32 v209, 0x1400, v209
	v_add_u32_e32 v224, 0xffffc080, v176
	v_add_u32_e32 v96, 0x80, v176
	s_waitcnt lgkmcnt(0)
	v_lshrrev_b32_e32 v81, 6, v224
	v_cmp_gt_i32_e32 vcc, s94, v96
	v_ashrrev_i32_e32 v80, 11, v96
	v_add_u32_e32 v81, 8, v81
	v_cndmask_b32_e32 v84, v81, v80, vcc
	v_mov_b64_e32 v[80:81], s[18:19]
	v_mad_i64_i32 v[80:81], s[12:13], v84, s75, v[80:81]
	v_mov_b64_e32 v[82:83], s[26:27]
	v_lshl_add_u64 v[92:93], v[172:173], 2, v[80:81]
	v_mad_i64_i32 v[84:85], s[12:13], v84, s75, v[82:83]
	global_load_dwordx4 v[80:83], v[92:93], off
	s_movk_i32 s6, 0x3fff
	v_cmp_lt_i32_e64 s[6:7], s6, v96
	s_and_b64 vcc, exec, s[0:1]
	s_cbranch_vccnz .LBB0_2101
	v_lshl_add_u64 v[64:65], v[84:85], 0, v[174:175]
	global_load_dwordx4 v[64:67], v[64:65], off
	s_nop 0
	global_load_dwordx4 v[86:89], v[178:179], off
	s_waitcnt vmcnt(1)
	v_pk_add_f32 v[66:67], v[66:67], 1.0 op_sel_hi:[1,0]
	v_pk_add_f32 v[64:65], v[64:65], 1.0 op_sel_hi:[1,0]
	s_waitcnt vmcnt(0)
	v_pk_mul_f32 v[66:67], v[88:89], v[66:67]
	v_pk_mul_f32 v[64:65], v[86:87], v[64:65]
	global_load_dwordx4 v[88:91], v[92:93], off offset:16
	s_and_b64 vcc, exec, s[0:1]
	v_lshl_add_u64 v[98:99], v[172:173], 2, v[84:85]
	s_cbranch_vccz .LBB0_2102

; DI u32x4 pack8(const float* v) { u32x4 w; w.x = pk2(v[0], v[1]); w.y = pk2(v[2], v[3]); w.z = pk2(v[4], v[5]); w.w = pk2(v[6], v[7]); return w; }
; #define xor16_32(s) xor16_32_l((s), fr + 16 * fq)
;     DI void operator()(AccRef acc, const Unit& u, int wr, int wc, int fr, int fq) const {
;     ...
;             for (int m = 0; m < 4; ++m) {
;                 const int row = rb + 16 * m;
;                 const float* xi = row < MP ? xin_p + (size_t)row * 1024 : xin_s + (size_t)(row - MP) * 1024;
;                 float s = 0.f;
; #pragma unroll
;                 for (int bj = 0; bj < 2; ++bj) {
;                     const int c = u.pn * 256 + bj * 128 + cl;
;                     float v[8];
; #pragma unroll
;                     for (int n = 0; n < 2; ++n) {
;                         const f32x4 x = *(const f32x4*)(xi + c + 4 * n);
;                         const f32x4 y = x + gt[bj][n] * acc[ai][bj][m][n];
;                         *(f32x4*)(xout + (size_t)row * 1024 + c + 4 * n) = y;
; #pragma unroll
;                         for (int j = 0; j < 4; ++j) { s += y[j] * y[j]; v[4 * n + j] = ap ? y[j] * gs[bj][n][j] : 0.f; }
;                     }
;                     if (ap) *(u32x4*)(ap + (size_t)row * 1024 + c) = pack8(v);
;                 }
;                 s = xor16_32(s);
;                 if (fq == 0) ssq[(size_t)row * 16 + u.pn * 4 + wc] = s;
;             }
.LBB0_2109:
	s_or_b64 exec, exec, s[6:7]
	s_waitcnt vmcnt(0)
	v_permlane32_swap_b32_e32 v228, v232
	v_permlane32_swap_b32_e32 v229, v233
	v_permlane32_swap_b32_e32 v230, v234
	v_permlane32_swap_b32_e32 v231, v235
	v_permlane32_swap_b32_e32 v236, v240
	v_permlane32_swap_b32_e32 v237, v241
	v_permlane32_swap_b32_e32 v238, v242
	v_permlane32_swap_b32_e32 v239, v243
	v_permlane16_swap_b32_e32 v228, v232
	v_permlane16_swap_b32_e32 v229, v233
	v_permlane16_swap_b32_e32 v230, v234
	v_permlane16_swap_b32_e32 v231, v235
	v_permlane16_swap_b32_e32 v236, v240
	v_permlane16_swap_b32_e32 v237, v241
	v_permlane16_swap_b32_e32 v238, v242
	v_permlane16_swap_b32_e32 v239, v243
	v_pk_fma_f32 v[60:61], v[60:61], v[80:81], v[228:229]
	v_pk_fma_f32 v[62:63], v[62:63], v[82:83], v[230:231]
	v_mul_f32_e32 v210, v61, v61
	v_fmac_f32_e32 v210, v60, v60
	v_fmac_f32_e32 v210, v62, v62
	v_fmac_f32_e32 v210, v63, v63
	v_pk_fma_f32 v[56:57], v[56:57], v[88:89], v[232:233]
	v_pk_fma_f32 v[58:59], v[58:59], v[90:91], v[234:235]
	v_fmac_f32_e32 v210, v56, v56
	v_fmac_f32_e32 v210, v57, v57
	v_fmac_f32_e32 v210, v58, v58
	v_fmac_f32_e32 v210, v59, v59
	v_pk_fma_f32 v[52:53], v[52:53], v[84:85], v[236:237]
	v_pk_fma_f32 v[54:55], v[54:55], v[86:87], v[238:239]
	v_fmac_f32_e32 v210, v52, v52
	v_fmac_f32_e32 v210, v53, v53
	v_fmac_f32_e32 v210, v54, v54
	v_fmac_f32_e32 v210, v55, v55
	v_pk_fma_f32 v[48:49], v[48:49], v[92:93], v[240:241]
	v_pk_fma_f32 v[50:51], v[50:51], v[94:95], v[242:243]
	v_fmac_f32_e32 v210, v48, v48
	v_fmac_f32_e32 v210, v49, v49
	v_fmac_f32_e32 v210, v50, v50
	v_fmac_f32_e32 v210, v51, v51
	s_cmp_lg_u64 s[0:1], 0
	s_cbranch_scc1 .Lnoap_D_5
	v_pk_mul_f32 v[228:229], v[64:65], v[60:61]
	v_pk_mul_f32 v[230:231], v[66:67], v[62:63]
	v_pk_mul_f32 v[232:233], v[72:73], v[56:57]
	v_pk_mul_f32 v[234:235], v[74:75], v[58:59]
	v_pk_mul_f32 v[236:237], v[68:69], v[52:53]
	v_pk_mul_f32 v[238:239], v[70:71], v[54:55]
	v_pk_mul_f32 v[240:241], v[76:77], v[48:49]
	v_pk_mul_f32 v[242:243], v[78:79], v[50:51]
	v_cvt_pk_bf16_f32 v228, v228, v229
	v_cvt_pk_bf16_f32 v229, v230, v231
	v_cvt_pk_bf16_f32 v230, v232, v233
	v_cvt_pk_bf16_f32 v231, v234, v235
	global_store_dwordx4 v208, v[228:231], s[28:29]
	v_cvt_pk_bf16_f32 v236, v236, v237
	v_cvt_pk_bf16_f32 v237, v238, v239
	v_cvt_pk_bf16_f32 v238, v240, v241
	v_cvt_pk_bf16_f32 v239, v242, v243
	global_store_dwordx4 v208, v[236:239], s[28:29] offset:256
.Lnoap_D_5:
	ds_bpermute_b32 v211, v214, v210
	v_permlane16_swap_b32_e32 v60, v56
	v_permlane16_swap_b32_e32 v61, v57
	v_permlane16_swap_b32_e32 v62, v58
	v_permlane16_swap_b32_e32 v63, v59
	v_permlane16_swap_b32_e32 v52, v48
	v_permlane16_swap_b32_e32 v53, v49
	v_permlane16_swap_b32_e32 v54, v50
	v_permlane16_swap_b32_e32 v55, v51
	v_permlane32_swap_b32_e32 v60, v56
	v_permlane32_swap_b32_e32 v61, v57
	v_permlane32_swap_b32_e32 v62, v58
	v_permlane32_swap_b32_e32 v63, v59
	v_permlane32_swap_b32_e32 v52, v48
	v_permlane32_swap_b32_e32 v53, v49
	v_permlane32_swap_b32_e32 v54, v50
	v_permlane32_swap_b32_e32 v55, v51
	global_store_dwordx4 v207, v[60:63], s[84:85]
	global_store_dwordx4 v207, v[56:59], s[84:85] offset:64
	global_store_dwordx4 v207, v[52:55], s[84:85] offset:512
	global_store_dwordx4 v207, v[48:51], s[84:85] offset:576
	v_add_u32_e32 v207, 0x10000, v207
	v_add_u32_e32 v206, 0x10000, v206
	global_load_dwordx4 v[232:235], v206, s[70:71] offset:64
	global_load_dwordx4 v[240:243], v206, s[70:71] offset:576
	global_load_dwordx4 v[228:231], v206, s[70:71]
	global_load_dwordx4 v[236:239], v206, s[70:71] offset:512
	s_waitcnt lgkmcnt(0)
	v_add_f32_e32 v211, v210, v211
	ds_bpermute_b32 v212, v215, v211
	v_add_u32_e32 v208, 0x8000, v208
	s_waitcnt lgkmcnt(0)
	v_add_f32_e32 v211, v211, v212
	s_mov_b64 exec, 0xffff
	global_store_dword v209, v211, s[72:73]
	s_mov_b64 exec, -1
	v_add_u32_e32 v209, 0x400, v209
	v_permlane32_swap_b32_e32 v244, v248
	v_permlane32_swap_b32_e32 v245, v249
	v_permlane32_swap_b32_e32 v246, v250
	v_permlane32_swap_b32_e32 v247, v251
	v_permlane32_swap_b32_e32 v216, v220
	v_permlane32_swap_b32_e32 v217, v221
	v_permlane32_swap_b32_e32 v218, v222
	v_permlane32_swap_b32_e32 v219, v223
	v_permlane16_swap_b32_e32 v244, v248
	v_permlane16_swap_b32_e32 v245, v249
	v_permlane16_swap_b32_e32 v246, v250
	v_permlane16_swap_b32_e32 v247, v251
	v_permlane16_swap_b32_e32 v216, v220
	v_permlane16_swap_b32_e32 v217, v221
	v_permlane16_swap_b32_e32 v218, v222
	v_permlane16_swap_b32_e32 v219, v223
	v_pk_fma_f32 v[44:45], v[44:45], v[80:81], v[244:245]
	v_pk_fma_f32 v[46:47], v[46:47], v[82:83], v[246:247]
	v_mul_f32_e32 v210, v45, v45
	v_fmac_f32_e32 v210, v44, v44
	v_fmac_f32_e32 v210, v46, v46
	v_fmac_f32_e32 v210, v47, v47
	v_pk_fma_f32 v[40:41], v[40:41], v[88:89], v[248:249]
	v_pk_fma_f32 v[42:43], v[42:43], v[90:91], v[250:251]
	v_fmac_f32_e32 v210, v40, v40
	v_fmac_f32_e32 v210, v41, v41
	v_fmac_f32_e32 v210, v42, v42
	v_fmac_f32_e32 v210, v43, v43
	v_pk_fma_f32 v[36:37], v[36:37], v[84:85], v[216:217]
	v_pk_fma_f32 v[38:39], v[38:39], v[86:87], v[218:219]
	v_fmac_f32_e32 v210, v36, v36
	v_fmac_f32_e32 v210, v37, v37
	v_fmac_f32_e32 v210, v38, v38
	v_fmac_f32_e32 v210, v39, v39
	v_pk_fma_f32 v[32:33], v[32:33], v[92:93], v[220:221]
	v_pk_fma_f32 v[34:35], v[34:35], v[94:95], v[222:223]
	v_fmac_f32_e32 v210, v32, v32
	v_fmac_f32_e32 v210, v33, v33
	v_fmac_f32_e32 v210, v34, v34
	v_fmac_f32_e32 v210, v35, v35
	s_cmp_lg_u64 s[0:1], 0
	s_cbranch_scc1 .Lnoap_D_6
	v_pk_mul_f32 v[244:245], v[64:65], v[44:45]
	v_pk_mul_f32 v[246:247], v[66:67], v[46:47]
	v_pk_mul_f32 v[248:249], v[72:73], v[40:41]
	v_pk_mul_f32 v[250:251], v[74:75], v[42:43]
	v_pk_mul_f32 v[216:217], v[68:69], v[36:37]
	v_pk_mul_f32 v[218:219], v[70:71], v[38:39]
	v_pk_mul_f32 v[220:221], v[76:77], v[32:33]
	v_pk_mul_f32 v[222:223], v[78:79], v[34:35]
	v_cvt_pk_bf16_f32 v244, v244, v245
	v_cvt_pk_bf16_f32 v245, v246, v247
	v_cvt_pk_bf16_f32 v246, v248, v249
	v_cvt_pk_bf16_f32 v247, v250, v251
	global_store_dwordx4 v208, v[244:247], s[28:29]
	v_cvt_pk_bf16_f32 v216, v216, v217
	v_cvt_pk_bf16_f32 v217, v218, v219
	v_cvt_pk_bf16_f32 v218, v220, v221
	v_cvt_pk_bf16_f32 v219, v222, v223
	global_store_dwordx4 v208, v[216:219], s[28:29] offset:256
; DI u32x4 pack8(const float* v) { u32x4 w; w.x = pk2(v[0], v[1]); w.y = pk2(v[2], v[3]); w.z = pk2(v[4], v[5]); w.w = pk2(v[6], v[7]); return w; }
; #define xor16_32(s) xor16_32_l((s), fr + 16 * fq)
;     DI void operator()(AccRef acc, const Unit& u, int wr, int wc, int fr, int fq) const {
;     ...
;             for (int m = 0; m < 4; ++m) {
;                 const int row = rb + 16 * m;
;                 const float* xi = row < MP ? xin_p + (size_t)row * 1024 : xin_s + (size_t)(row - MP) * 1024;
;                 float s = 0.f;
; #pragma unroll
;                 for (int bj = 0; bj < 2; ++bj) {
;                     const int c = u.pn * 256 + bj * 128 + cl;
;                     float v[8];
; #pragma unroll
;                     for (int n = 0; n < 2; ++n) {
;                         const f32x4 x = *(const f32x4*)(xi + c + 4 * n);
;                         const f32x4 y = x + gt[bj][n] * acc[ai][bj][m][n];
;                         *(f32x4*)(xout + (size_t)row * 1024 + c + 4 * n) = y;
; #pragma unroll
;                         for (int j = 0; j < 4; ++j) { s += y[j] * y[j]; v[4 * n + j] = ap ? y[j] * gs[bj][n][j] : 0.f; }
;                     }
;                     if (ap) *(u32x4*)(ap + (size_t)row * 1024 + c) = pack8(v);
;                 }
;                 s = xor16_32(s);
;                 if (fq == 0) ssq[(size_t)row * 16 + u.pn * 4 + wc] = s;
;             }
.Lnoap_D_6:
	ds_bpermute_b32 v211, v214, v210
	v_permlane16_swap_b32_e32 v44, v40
	v_permlane16_swap_b32_e32 v45, v41
	v_permlane16_swap_b32_e32 v46, v42
	v_permlane16_swap_b32_e32 v47, v43
	v_permlane16_swap_b32_e32 v36, v32
	v_permlane16_swap_b32_e32 v37, v33
	v_permlane16_swap_b32_e32 v38, v34
	v_permlane16_swap_b32_e32 v39, v35
	v_permlane32_swap_b32_e32 v44, v40
	v_permlane32_swap_b32_e32 v45, v41
	v_permlane32_swap_b32_e32 v46, v42
	v_permlane32_swap_b32_e32 v47, v43
	v_permlane32_swap_b32_e32 v36, v32
	v_permlane32_swap_b32_e32 v37, v33
	v_permlane32_swap_b32_e32 v38, v34
	v_permlane32_swap_b32_e32 v39, v35
	global_store_dwordx4 v207, v[44:47], s[84:85]
	global_store_dwordx4 v207, v[40:43], s[84:85] offset:64
	global_store_dwordx4 v207, v[36:39], s[84:85] offset:512
	global_store_dwordx4 v207, v[32:35], s[84:85] offset:576
	v_add_u32_e32 v207, 0x10000, v207
	v_add_u32_e32 v206, 0x10000, v206
	global_load_dwordx4 v[248:251], v206, s[70:71] offset:64
	global_load_dwordx4 v[220:223], v206, s[70:71] offset:576
	global_load_dwordx4 v[244:247], v206, s[70:71]
	global_load_dwordx4 v[216:219], v206, s[70:71] offset:512
	s_waitcnt lgkmcnt(0)
	v_add_f32_e32 v211, v210, v211
	ds_bpermute_b32 v212, v215, v211
	v_add_u32_e32 v208, 0x8000, v208
	s_waitcnt lgkmcnt(0)
	v_add_f32_e32 v211, v211, v212
	s_mov_b64 exec, 0xffff
	global_store_dword v209, v211, s[72:73]
	s_mov_b64 exec, -1
	v_add_u32_e32 v209, 0x400, v209
	s_waitcnt vmcnt(10)
	v_permlane32_swap_b32_e32 v228, v232
	v_permlane32_swap_b32_e32 v229, v233
	v_permlane32_swap_b32_e32 v230, v234
	v_permlane32_swap_b32_e32 v231, v235
	v_permlane32_swap_b32_e32 v236, v240
	v_permlane32_swap_b32_e32 v237, v241
	v_permlane32_swap_b32_e32 v238, v242
	v_permlane32_swap_b32_e32 v239, v243
	v_permlane16_swap_b32_e32 v228, v232
	v_permlane16_swap_b32_e32 v229, v233
	v_permlane16_swap_b32_e32 v230, v234
	v_permlane16_swap_b32_e32 v231, v235
	v_permlane16_swap_b32_e32 v236, v240
	v_permlane16_swap_b32_e32 v237, v241
	v_permlane16_swap_b32_e32 v238, v242
	v_permlane16_swap_b32_e32 v239, v243
	v_pk_fma_f32 v[28:29], v[28:29], v[80:81], v[228:229]
	v_pk_fma_f32 v[30:31], v[30:31], v[82:83], v[230:231]
	v_mul_f32_e32 v210, v29, v29
	v_fmac_f32_e32 v210, v28, v28
	v_fmac_f32_e32 v210, v30, v30
	v_fmac_f32_e32 v210, v31, v31
	v_pk_fma_f32 v[24:25], v[24:25], v[88:89], v[232:233]
	v_pk_fma_f32 v[26:27], v[26:27], v[90:91], v[234:235]
	v_fmac_f32_e32 v210, v24, v24
	v_fmac_f32_e32 v210, v25, v25
	v_fmac_f32_e32 v210, v26, v26
	v_fmac_f32_e32 v210, v27, v27
	v_pk_fma_f32 v[20:21], v[20:21], v[84:85], v[236:237]
	v_pk_fma_f32 v[22:23], v[22:23], v[86:87], v[238:239]
	v_fmac_f32_e32 v210, v20, v20
	v_fmac_f32_e32 v210, v21, v21
	v_fmac_f32_e32 v210, v22, v22
	v_fmac_f32_e32 v210, v23, v23
	v_pk_fma_f32 v[16:17], v[16:17], v[92:93], v[240:241]
	v_pk_fma_f32 v[18:19], v[18:19], v[94:95], v[242:243]
	v_fmac_f32_e32 v210, v16, v16
	v_fmac_f32_e32 v210, v17, v17
	v_fmac_f32_e32 v210, v18, v18
	v_fmac_f32_e32 v210, v19, v19
	s_cmp_lg_u64 s[0:1], 0
	s_cbranch_scc1 .Lnoap_D_7
	v_pk_mul_f32 v[228:229], v[64:65], v[28:29]
	v_pk_mul_f32 v[230:231], v[66:67], v[30:31]
	v_pk_mul_f32 v[232:233], v[72:73], v[24:25]
	v_pk_mul_f32 v[234:235], v[74:75], v[26:27]
	v_pk_mul_f32 v[236:237], v[68:69], v[20:21]
	v_pk_mul_f32 v[238:239], v[70:71], v[22:23]
	v_pk_mul_f32 v[240:241], v[76:77], v[16:17]
	v_pk_mul_f32 v[242:243], v[78:79], v[18:19]
	v_cvt_pk_bf16_f32 v228, v228, v229
	v_cvt_pk_bf16_f32 v229, v230, v231
	v_cvt_pk_bf16_f32 v230, v232, v233
	v_cvt_pk_bf16_f32 v231, v234, v235
	global_store_dwordx4 v208, v[228:231], s[28:29]
	v_cvt_pk_bf16_f32 v236, v236, v237
	v_cvt_pk_bf16_f32 v237, v238, v239
	v_cvt_pk_bf16_f32 v238, v240, v241
	v_cvt_pk_bf16_f32 v239, v242, v243
	global_store_dwordx4 v208, v[236:239], s[28:29] offset:256
; DI u32x4 pack8(const float* v) { u32x4 w; w.x = pk2(v[0], v[1]); w.y = pk2(v[2], v[3]); w.z = pk2(v[4], v[5]); w.w = pk2(v[6], v[7]); return w; }
; #define xor16_32(s) xor16_32_l((s), fr + 16 * fq)
;     DI void operator()(AccRef acc, const Unit& u, int wr, int wc, int fr, int fq) const {
;     ...
;             for (int m = 0; m < 4; ++m) {
;                 const int row = rb + 16 * m;
;                 const float* xi = row < MP ? xin_p + (size_t)row * 1024 : xin_s + (size_t)(row - MP) * 1024;
;                 float s = 0.f;
; #pragma unroll
;                 for (int bj = 0; bj < 2; ++bj) {
;                     const int c = u.pn * 256 + bj * 128 + cl;
;                     float v[8];
; #pragma unroll
;                     for (int n = 0; n < 2; ++n) {
;                         const f32x4 x = *(const f32x4*)(xi + c + 4 * n);
;                         const f32x4 y = x + gt[bj][n] * acc[ai][bj][m][n];
;                         *(f32x4*)(xout + (size_t)row * 1024 + c + 4 * n) = y;
; #pragma unroll
;                         for (int j = 0; j < 4; ++j) { s += y[j] * y[j]; v[4 * n + j] = ap ? y[j] * gs[bj][n][j] : 0.f; }
;                     }
;                     if (ap) *(u32x4*)(ap + (size_t)row * 1024 + c) = pack8(v);
;                 }
;                 s = xor16_32(s);
;                 if (fq == 0) ssq[(size_t)row * 16 + u.pn * 4 + wc] = s;
;             }
.Lnoap_D_7:
	ds_bpermute_b32 v211, v214, v210
	v_permlane16_swap_b32_e32 v28, v24
	v_permlane16_swap_b32_e32 v29, v25
	v_permlane16_swap_b32_e32 v30, v26
	v_permlane16_swap_b32_e32 v31, v27
	v_permlane16_swap_b32_e32 v20, v16
	v_permlane16_swap_b32_e32 v21, v17
	v_permlane16_swap_b32_e32 v22, v18
	v_permlane16_swap_b32_e32 v23, v19
	v_permlane32_swap_b32_e32 v28, v24
	v_permlane32_swap_b32_e32 v29, v25
	v_permlane32_swap_b32_e32 v30, v26
	v_permlane32_swap_b32_e32 v31, v27
	v_permlane32_swap_b32_e32 v20, v16
	v_permlane32_swap_b32_e32 v21, v17
	v_permlane32_swap_b32_e32 v22, v18
	v_permlane32_swap_b32_e32 v23, v19
	global_store_dwordx4 v207, v[28:31], s[84:85]
	global_store_dwordx4 v207, v[24:27], s[84:85] offset:64
	global_store_dwordx4 v207, v[20:23], s[84:85] offset:512
	global_store_dwordx4 v207, v[16:19], s[84:85] offset:576
	v_add_u32_e32 v207, 0x10000, v207
	s_waitcnt lgkmcnt(0)
	v_add_f32_e32 v211, v210, v211
	ds_bpermute_b32 v212, v215, v211
	v_add_u32_e32 v208, 0x8000, v208
	s_waitcnt lgkmcnt(0)
	v_add_f32_e32 v211, v211, v212
	s_mov_b64 exec, 0xffff
	global_store_dword v209, v211, s[72:73]
	s_mov_b64 exec, -1
	v_add_u32_e32 v209, 0x400, v209
	s_waitcnt vmcnt(6)
	v_permlane32_swap_b32_e32 v244, v248
	v_permlane32_swap_b32_e32 v245, v249
	v_permlane32_swap_b32_e32 v246, v250
	v_permlane32_swap_b32_e32 v247, v251
	v_permlane32_swap_b32_e32 v216, v220
	v_permlane32_swap_b32_e32 v217, v221
	v_permlane32_swap_b32_e32 v218, v222
	v_permlane32_swap_b32_e32 v219, v223
	v_permlane16_swap_b32_e32 v244, v248
	v_permlane16_swap_b32_e32 v245, v249
	v_permlane16_swap_b32_e32 v246, v250
	v_permlane16_swap_b32_e32 v247, v251
	v_permlane16_swap_b32_e32 v216, v220
	v_permlane16_swap_b32_e32 v217, v221
	v_permlane16_swap_b32_e32 v218, v222
	v_permlane16_swap_b32_e32 v219, v223
	v_pk_fma_f32 v[12:13], v[12:13], v[80:81], v[244:245]
	v_pk_fma_f32 v[14:15], v[14:15], v[82:83], v[246:247]
	v_mul_f32_e32 v210, v13, v13
	v_fmac_f32_e32 v210, v12, v12
	v_fmac_f32_e32 v210, v14, v14
	v_fmac_f32_e32 v210, v15, v15
	v_pk_fma_f32 v[8:9], v[8:9], v[88:89], v[248:249]
	v_pk_fma_f32 v[10:11], v[10:11], v[90:91], v[250:251]
	v_fmac_f32_e32 v210, v8, v8
	v_fmac_f32_e32 v210, v9, v9
	v_fmac_f32_e32 v210, v10, v10
	v_fmac_f32_e32 v210, v11, v11
	v_pk_fma_f32 v[4:5], v[4:5], v[84:85], v[216:217]
	v_pk_fma_f32 v[6:7], v[6:7], v[86:87], v[218:219]
	v_fmac_f32_e32 v210, v4, v4
	v_fmac_f32_e32 v210, v5, v5
	v_fmac_f32_e32 v210, v6, v6
	v_fmac_f32_e32 v210, v7, v7
	v_pk_fma_f32 v[0:1], v[0:1], v[92:93], v[220:221]
	v_pk_fma_f32 v[2:3], v[2:3], v[94:95], v[222:223]
	v_fmac_f32_e32 v210, v0, v0
	v_fmac_f32_e32 v210, v1, v1
	v_fmac_f32_e32 v210, v2, v2
	v_fmac_f32_e32 v210, v3, v3
	s_cmp_lg_u64 s[0:1], 0
	s_cbranch_scc1 .Lnoap_D_8
	v_pk_mul_f32 v[244:245], v[64:65], v[12:13]
	v_pk_mul_f32 v[246:247], v[66:67], v[14:15]
	v_pk_mul_f32 v[248:249], v[72:73], v[8:9]
	v_pk_mul_f32 v[250:251], v[74:75], v[10:11]
	v_pk_mul_f32 v[216:217], v[68:69], v[4:5]
	v_pk_mul_f32 v[218:219], v[70:71], v[6:7]
	v_pk_mul_f32 v[220:221], v[76:77], v[0:1]
	v_pk_mul_f32 v[222:223], v[78:79], v[2:3]
	v_cvt_pk_bf16_f32 v244, v244, v245
	v_cvt_pk_bf16_f32 v245, v246, v247
	v_cvt_pk_bf16_f32 v246, v248, v249
	v_cvt_pk_bf16_f32 v247, v250, v251
	global_store_dwordx4 v208, v[244:247], s[28:29]
	v_cvt_pk_bf16_f32 v216, v216, v217
	v_cvt_pk_bf16_f32 v217, v218, v219
	v_cvt_pk_bf16_f32 v218, v220, v221
	v_cvt_pk_bf16_f32 v219, v222, v223
	global_store_dwordx4 v208, v[216:219], s[28:29] offset:256
.Lnoap_D_8:
	ds_bpermute_b32 v211, v214, v210
	v_permlane16_swap_b32_e32 v12, v8
	v_permlane16_swap_b32_e32 v13, v9
	v_permlane16_swap_b32_e32 v14, v10
	v_permlane16_swap_b32_e32 v15, v11
	v_permlane16_swap_b32_e32 v4, v0
	v_permlane16_swap_b32_e32 v5, v1
	v_permlane16_swap_b32_e32 v6, v2
	v_permlane16_swap_b32_e32 v7, v3
	v_permlane32_swap_b32_e32 v12, v8
	v_permlane32_swap_b32_e32 v13, v9
	v_permlane32_swap_b32_e32 v14, v10
	v_permlane32_swap_b32_e32 v15, v11
	v_permlane32_swap_b32_e32 v4, v0
	v_permlane32_swap_b32_e32 v5, v1
	v_permlane32_swap_b32_e32 v6, v2
	v_permlane32_swap_b32_e32 v7, v3
	global_store_dwordx4 v207, v[12:15], s[84:85]
	global_store_dwordx4 v207, v[8:11], s[84:85] offset:64
	global_store_dwordx4 v207, v[4:7], s[84:85] offset:512
	global_store_dwordx4 v207, v[0:3], s[84:85] offset:576
	s_waitcnt lgkmcnt(0)
	v_add_f32_e32 v211, v210, v211
	ds_bpermute_b32 v212, v215, v211
	s_waitcnt lgkmcnt(0)
	v_add_f32_e32 v211, v211, v212
	s_mov_b64 exec, 0xffff
	global_store_dword v209, v211, s[72:73]
	s_mov_b64 exec, -1
	s_and_b64 vcc, exec, s[2:3]
	s_mov_b64 s[2:3], -1
	s_cbranch_vccnz .LBB0_2034
	s_andn2_b64 vcc, exec, s[8:9]
	s_cbranch_vccnz .LBB0_2033
	s_barrier
	s_branch .LBB0_2033
